# combination plus GEMV stream with three row sets in flight and GLU epilogue with its y loads issued together
# speedup vs baseline: 1.0219x; 1.0019x over previous
.LBB0_115:
	v_lshl_add_u32 v148, s76, 8, v5
	v_lshl_or_b32 v146, s0, 8, v153
	v_ashrrev_i32_e32 v149, 31, v148
	v_ashrrev_i32_e32 v147, 31, v146
	v_lshlrev_b64 v[156:157], 11, v[148:149]
	v_lshl_add_u64 v[156:157], s[10:11], 0, v[156:157]
	v_lshlrev_b64 v[146:147], 1, v[146:147]
	v_lshl_add_u64 v[160:161], v[156:157], 0, v[146:147]
	global_load_dwordx4 v[156:159], v[160:161], off
	global_load_dwordx4 v[172:175], v[160:161], off offset:256
	s_mov_b64 vcc, 0x8000
	v_lshl_add_u64 v[232:233], v[160:161], 0, vcc
	global_load_dwordx4 v[176:179], v[232:233], off
	global_load_dwordx4 v[180:183], v[232:233], off offset:256
	s_mov_b64 vcc, 0x10000
	v_lshl_add_u64 v[232:233], v[160:161], 0, vcc
	global_load_dwordx4 v[184:187], v[232:233], off
	global_load_dwordx4 v[188:191], v[232:233], off offset:256
	s_mov_b64 vcc, 0x18000
	v_lshl_add_u64 v[232:233], v[160:161], 0, vcc
	global_load_dwordx4 v[192:195], v[232:233], off
	global_load_dwordx4 v[196:199], v[232:233], off offset:256
	s_mov_b64 vcc, 0x40000
	v_lshl_add_u64 v[232:233], v[160:161], 0, vcc
	global_load_dwordx4 v[200:203], v[232:233], off
	global_load_dwordx4 v[204:207], v[232:233], off offset:256
	s_mov_b64 vcc, 0x48000
	v_lshl_add_u64 v[232:233], v[160:161], 0, vcc
	global_load_dwordx4 v[208:211], v[232:233], off
	global_load_dwordx4 v[212:215], v[232:233], off offset:256
	s_mov_b64 vcc, 0x50000
	v_lshl_add_u64 v[232:233], v[160:161], 0, vcc
	global_load_dwordx4 v[216:219], v[232:233], off
	global_load_dwordx4 v[220:223], v[232:233], off offset:256
	s_mov_b64 vcc, 0x58000
	v_lshl_add_u64 v[232:233], v[160:161], 0, vcc
	global_load_dwordx4 v[224:227], v[232:233], off
	global_load_dwordx4 v[228:231], v[232:233], off offset:256
	v_mul_f32_e32 v130, 0xbfb8aa3b, v130
	v_mul_f32_e32 v131, 0xbfb8aa3b, v131
	v_exp_f32_e32 v130, v130
	v_exp_f32_e32 v131, v131
	v_mul_f32_e32 v126, 0xbfb8aa3b, v126
	v_mul_f32_e32 v127, 0xbfb8aa3b, v127
	v_add_f32_e32 v130, 1.0, v130
	v_add_f32_e32 v131, 1.0, v131
	v_rcp_f32_e32 v130, v130
	v_rcp_f32_e32 v131, v131
	v_exp_f32_e32 v126, v126
	v_exp_f32_e32 v127, v127
	v_mul_f32_e32 v122, 0xbfb8aa3b, v122
	v_mul_f32_e32 v123, 0xbfb8aa3b, v123
	v_add_f32_e32 v126, 1.0, v126
	v_add_f32_e32 v127, 1.0, v127
	v_rcp_f32_e32 v126, v126
	v_rcp_f32_e32 v127, v127
	v_exp_f32_e32 v122, v122
	v_exp_f32_e32 v123, v123
	v_mul_f32_e32 v118, 0xbfb8aa3b, v118
	v_mul_f32_e32 v119, 0xbfb8aa3b, v119
	v_add_f32_e32 v122, 1.0, v122
	v_add_f32_e32 v123, 1.0, v123
	v_rcp_f32_e32 v122, v122
	v_rcp_f32_e32 v123, v123
	v_exp_f32_e32 v118, v118
	v_exp_f32_e32 v119, v119
	v_mul_f32_e32 v114, 0xbfb8aa3b, v114
	v_mul_f32_e32 v115, 0xbfb8aa3b, v115
	v_add_f32_e32 v118, 1.0, v118
	v_add_f32_e32 v119, 1.0, v119
	v_rcp_f32_e32 v118, v118
	v_rcp_f32_e32 v119, v119
	v_exp_f32_e32 v114, v114
	v_exp_f32_e32 v115, v115
	v_mul_f32_e32 v110, 0xbfb8aa3b, v110
	v_mul_f32_e32 v111, 0xbfb8aa3b, v111
	v_add_f32_e32 v114, 1.0, v114
	v_add_f32_e32 v115, 1.0, v115
	v_rcp_f32_e32 v114, v114
	v_rcp_f32_e32 v115, v115
	v_exp_f32_e32 v110, v110
	v_exp_f32_e32 v111, v111
	v_mul_f32_e32 v106, 0xbfb8aa3b, v106
	v_mul_f32_e32 v107, 0xbfb8aa3b, v107
	v_add_f32_e32 v110, 1.0, v110
	v_add_f32_e32 v111, 1.0, v111
	v_rcp_f32_e32 v110, v110
	v_rcp_f32_e32 v111, v111
	v_exp_f32_e32 v106, v106
	v_exp_f32_e32 v107, v107
	v_mul_f32_e32 v102, 0xbfb8aa3b, v102
	v_mul_f32_e32 v103, 0xbfb8aa3b, v103
	v_add_f32_e32 v106, 1.0, v106
	v_add_f32_e32 v107, 1.0, v107
	v_rcp_f32_e32 v106, v106
	v_rcp_f32_e32 v107, v107
	v_exp_f32_e32 v102, v102
	v_exp_f32_e32 v103, v103
	v_mul_f32_e32 v98, 0xbfb8aa3b, v98
	v_mul_f32_e32 v99, 0xbfb8aa3b, v99
	v_add_f32_e32 v102, 1.0, v102
	v_add_f32_e32 v103, 1.0, v103
	v_rcp_f32_e32 v102, v102
	v_rcp_f32_e32 v103, v103
	v_exp_f32_e32 v98, v98
	v_exp_f32_e32 v99, v99
	v_mul_f32_e32 v94, 0xbfb8aa3b, v94
	v_mul_f32_e32 v95, 0xbfb8aa3b, v95
	v_add_f32_e32 v98, 1.0, v98
	v_add_f32_e32 v99, 1.0, v99
	v_rcp_f32_e32 v98, v98
	v_rcp_f32_e32 v99, v99
	v_exp_f32_e32 v94, v94
	v_exp_f32_e32 v95, v95
	v_mul_f32_e32 v90, 0xbfb8aa3b, v90
	v_mul_f32_e32 v91, 0xbfb8aa3b, v91
	v_add_f32_e32 v94, 1.0, v94
	s_waitcnt vmcnt(0)
	v_lshlrev_b32_e32 v162, 16, v156
	v_and_b32_e32 v163, 0xffff0000, v156
	v_pk_mul_f32 v[130:131], v[130:131], v[162:163]
	v_lshlrev_b32_e32 v156, 16, v157
	v_cvt_pk_bf16_f32 v130, v130, v131
	v_mul_f32_e32 v131, 0xbfb8aa3b, v132
	v_exp_f32_e32 v131, v131
	v_and_b32_e32 v157, 0xffff0000, v157
	v_add_f32_e32 v95, 1.0, v95
	v_rcp_f32_e32 v94, v94
	v_add_f32_e32 v131, 1.0, v131
	v_rcp_f32_e32 v132, v131
	v_mul_f32_e32 v131, 0xbfb8aa3b, v133
	v_exp_f32_e32 v131, v131
	v_rcp_f32_e32 v95, v95
	v_exp_f32_e32 v90, v90
	v_exp_f32_e32 v91, v91
	v_add_f32_e32 v131, 1.0, v131
	v_rcp_f32_e32 v133, v131
	v_add_f32_e32 v90, 1.0, v90
	v_add_f32_e32 v91, 1.0, v91
	v_rcp_f32_e32 v90, v90
	v_pk_mul_f32 v[132:133], v[132:133], v[156:157]
	v_rcp_f32_e32 v91, v91
	v_cvt_pk_bf16_f32 v131, v132, v133
	v_lshlrev_b32_e32 v132, 16, v158
	v_and_b32_e32 v133, 0xffff0000, v158
	v_pk_mul_f32 v[126:127], v[126:127], v[132:133]
	v_mul_f32_e32 v86, 0xbfb8aa3b, v86
	v_cvt_pk_bf16_f32 v132, v126, v127
	v_mul_f32_e32 v126, 0xbfb8aa3b, v128
	v_mul_f32_e32 v127, 0xbfb8aa3b, v129
	v_exp_f32_e32 v126, v126
	v_exp_f32_e32 v127, v127
	v_lshlrev_b32_e32 v128, 16, v159
	v_and_b32_e32 v129, 0xffff0000, v159
	v_add_f32_e32 v126, 1.0, v126
	v_add_f32_e32 v127, 1.0, v127
	v_rcp_f32_e32 v126, v126
	v_rcp_f32_e32 v127, v127
	v_mul_f32_e32 v87, 0xbfb8aa3b, v87
	v_exp_f32_e32 v86, v86
	v_exp_f32_e32 v87, v87
	v_pk_mul_f32 v[126:127], v[126:127], v[128:129]
	v_mul_f32_e32 v82, 0xbfb8aa3b, v82
	v_cvt_pk_bf16_f32 v133, v126, v127
	v_lshlrev_b64 v[126:127], 12, v[148:149]
	v_lshl_add_u64 v[126:127], s[6:7], 0, v[126:127]
	v_lshl_add_u64 v[156:157], v[126:127], 0, v[146:147]
	s_nop 1
	v_mov_b32_e32 v126, v172
	v_mov_b32_e32 v127, v173
	v_mov_b32_e32 v128, v174
	v_mov_b32_e32 v129, v175
	v_add_f32_e32 v86, 1.0, v86
	global_store_dwordx4 v[156:157], v[130:133], off
	v_add_f32_e32 v87, 1.0, v87
	v_rcp_f32_e32 v86, v86
	v_rcp_f32_e32 v87, v87
	v_mul_f32_e32 v83, 0xbfb8aa3b, v83
	v_exp_f32_e32 v82, v82
	v_exp_f32_e32 v83, v83
	v_mul_f32_e32 v78, 0xbfb8aa3b, v78
	v_mul_f32_e32 v79, 0xbfb8aa3b, v79
	v_add_f32_e32 v82, 1.0, v82
	v_add_f32_e32 v83, 1.0, v83
	v_rcp_f32_e32 v82, v82
	v_rcp_f32_e32 v83, v83
	v_exp_f32_e32 v78, v78
	v_exp_f32_e32 v79, v79
	v_mul_f32_e32 v74, 0xbfb8aa3b, v74
	v_mul_f32_e32 v75, 0xbfb8aa3b, v75
	v_add_f32_e32 v78, 1.0, v78
	v_add_f32_e32 v79, 1.0, v79
	v_rcp_f32_e32 v78, v78
	v_rcp_f32_e32 v79, v79
	v_exp_f32_e32 v74, v74
	v_exp_f32_e32 v75, v75
	v_mul_f32_e32 v70, 0xbfb8aa3b, v70
	v_mul_f32_e32 v71, 0xbfb8aa3b, v71
	v_add_f32_e32 v74, 1.0, v74
	v_add_f32_e32 v75, 1.0, v75
	v_rcp_f32_e32 v74, v74
	v_rcp_f32_e32 v75, v75
	v_exp_f32_e32 v70, v70
	v_exp_f32_e32 v71, v71
	v_mul_f32_e32 v66, 0xbfb8aa3b, v66
	v_mul_f32_e32 v67, 0xbfb8aa3b, v67
	v_add_f32_e32 v70, 1.0, v70
	v_add_f32_e32 v71, 1.0, v71
	v_rcp_f32_e32 v70, v70
	v_rcp_f32_e32 v71, v71
	v_exp_f32_e32 v66, v66
	v_exp_f32_e32 v67, v67
	v_mul_f32_e32 v62, 0xbfb8aa3b, v62
	v_mul_f32_e32 v63, 0xbfb8aa3b, v63
	v_add_f32_e32 v66, 1.0, v66
	v_add_f32_e32 v67, 1.0, v67
	v_rcp_f32_e32 v66, v66
	v_rcp_f32_e32 v67, v67
	v_exp_f32_e32 v62, v62
	v_exp_f32_e32 v63, v63
	v_mul_f32_e32 v58, 0xbfb8aa3b, v58
	v_mul_f32_e32 v59, 0xbfb8aa3b, v59
	v_add_f32_e32 v62, 1.0, v62
	v_add_f32_e32 v63, 1.0, v63
	v_rcp_f32_e32 v62, v62
	v_rcp_f32_e32 v63, v63
	v_exp_f32_e32 v58, v58
	v_exp_f32_e32 v59, v59
	v_mul_f32_e32 v54, 0xbfb8aa3b, v54
	v_mul_f32_e32 v55, 0xbfb8aa3b, v55
	v_add_f32_e32 v58, 1.0, v58
	v_add_f32_e32 v59, 1.0, v59
	v_rcp_f32_e32 v58, v58
	v_rcp_f32_e32 v59, v59
	v_exp_f32_e32 v54, v54
	v_exp_f32_e32 v55, v55
	v_mul_f32_e32 v50, 0xbfb8aa3b, v50
	v_mul_f32_e32 v51, 0xbfb8aa3b, v51
	v_add_f32_e32 v54, 1.0, v54
	v_add_f32_e32 v55, 1.0, v55
	v_rcp_f32_e32 v54, v54
	v_rcp_f32_e32 v55, v55
	v_exp_f32_e32 v50, v50
	v_exp_f32_e32 v51, v51
	v_mul_f32_e32 v46, 0xbfb8aa3b, v46
	v_mul_f32_e32 v47, 0xbfb8aa3b, v47
	v_add_f32_e32 v50, 1.0, v50
	v_add_f32_e32 v51, 1.0, v51
	v_rcp_f32_e32 v50, v50
	v_rcp_f32_e32 v51, v51
	v_exp_f32_e32 v46, v46
	s_nop 0
	v_lshlrev_b32_e32 v130, 16, v126
	v_and_b32_e32 v131, 0xffff0000, v126
	v_pk_mul_f32 v[122:123], v[122:123], v[130:131]
	v_lshlrev_b32_e32 v126, 16, v127
	v_cvt_pk_bf16_f32 v122, v122, v123
	v_mul_f32_e32 v123, 0xbfb8aa3b, v124
	v_exp_f32_e32 v123, v123
	v_and_b32_e32 v127, 0xffff0000, v127
	v_exp_f32_e32 v47, v47
	v_add_f32_e32 v46, 1.0, v46
	v_add_f32_e32 v123, 1.0, v123
	v_rcp_f32_e32 v124, v123
	v_mul_f32_e32 v123, 0xbfb8aa3b, v125
	v_exp_f32_e32 v123, v123
	v_add_f32_e32 v47, 1.0, v47
	v_rcp_f32_e32 v46, v46
	v_rcp_f32_e32 v47, v47
	v_add_f32_e32 v123, 1.0, v123
	v_rcp_f32_e32 v125, v123
	v_mul_f32_e32 v42, 0xbfb8aa3b, v42
	v_mul_f32_e32 v43, 0xbfb8aa3b, v43
	v_exp_f32_e32 v42, v42
	v_pk_mul_f32 v[124:125], v[124:125], v[126:127]
	v_exp_f32_e32 v43, v43
	v_cvt_pk_bf16_f32 v123, v124, v125
	v_lshlrev_b32_e32 v124, 16, v128
	v_and_b32_e32 v125, 0xffff0000, v128
	v_pk_mul_f32 v[118:119], v[118:119], v[124:125]
	v_add_f32_e32 v42, 1.0, v42
	v_cvt_pk_bf16_f32 v124, v118, v119
	v_mul_f32_e32 v118, 0xbfb8aa3b, v120
	v_mul_f32_e32 v119, 0xbfb8aa3b, v121
	v_exp_f32_e32 v118, v118
	v_exp_f32_e32 v119, v119
	v_lshlrev_b32_e32 v120, 16, v129
	v_and_b32_e32 v121, 0xffff0000, v129
	v_add_f32_e32 v118, 1.0, v118
	v_add_f32_e32 v119, 1.0, v119
	v_rcp_f32_e32 v118, v118
	v_rcp_f32_e32 v119, v119
	v_add_f32_e32 v43, 1.0, v43
	v_rcp_f32_e32 v42, v42
	v_rcp_f32_e32 v43, v43
	v_pk_mul_f32 v[118:119], v[118:119], v[120:121]
	v_mul_f32_e32 v38, 0xbfb8aa3b, v38
	v_cvt_pk_bf16_f32 v125, v118, v119
	global_store_dwordx4 v[156:157], v[122:125], off offset:256
	v_mul_f32_e32 v39, 0xbfb8aa3b, v39
	v_exp_f32_e32 v38, v38
	v_or_b32_e32 v122, 16, v148
	v_ashrrev_i32_e32 v123, 31, v122
	v_lshlrev_b64 v[118:119], 11, v[122:123]
	v_lshl_add_u64 v[118:119], s[10:11], 0, v[118:119]
	v_lshl_add_u64 v[124:125], v[118:119], 0, v[146:147]
	s_nop 1
	v_mov_b32_e32 v118, v176
	v_mov_b32_e32 v119, v177
	v_mov_b32_e32 v120, v178
	v_mov_b32_e32 v121, v179
	v_exp_f32_e32 v39, v39
	v_add_f32_e32 v38, 1.0, v38
	v_rcp_f32_e32 v38, v38
	v_mul_f32_e32 v34, 0xbfb8aa3b, v34
	v_add_f32_e32 v39, 1.0, v39
	v_rcp_f32_e32 v39, v39
	v_mul_f32_e32 v35, 0xbfb8aa3b, v35
	v_exp_f32_e32 v34, v34
	v_exp_f32_e32 v35, v35
	v_mul_f32_e32 v30, 0xbfb8aa3b, v30
	v_mul_f32_e32 v31, 0xbfb8aa3b, v31
	v_add_f32_e32 v34, 1.0, v34
	v_add_f32_e32 v35, 1.0, v35
	v_rcp_f32_e32 v34, v34
	v_rcp_f32_e32 v35, v35
	v_exp_f32_e32 v30, v30
	v_exp_f32_e32 v31, v31
	v_mul_f32_e32 v26, 0xbfb8aa3b, v26
	v_mul_f32_e32 v27, 0xbfb8aa3b, v27
	v_add_f32_e32 v30, 1.0, v30
	v_add_f32_e32 v31, 1.0, v31
	v_rcp_f32_e32 v30, v30
	v_rcp_f32_e32 v31, v31
	v_exp_f32_e32 v26, v26
	v_exp_f32_e32 v27, v27
	v_mul_f32_e32 v22, 0xbfb8aa3b, v22
	v_mul_f32_e32 v23, 0xbfb8aa3b, v23
	v_add_f32_e32 v26, 1.0, v26
	v_add_f32_e32 v27, 1.0, v27
	v_rcp_f32_e32 v26, v26
	v_rcp_f32_e32 v27, v27
	v_exp_f32_e32 v22, v22
	v_exp_f32_e32 v23, v23
	v_mul_f32_e32 v18, 0xbfb8aa3b, v18
	v_mul_f32_e32 v19, 0xbfb8aa3b, v19
	v_add_f32_e32 v22, 1.0, v22
	v_add_f32_e32 v23, 1.0, v23
	v_rcp_f32_e32 v22, v22
	v_rcp_f32_e32 v23, v23
	v_exp_f32_e32 v18, v18
	v_exp_f32_e32 v19, v19
	v_mul_f32_e32 v10, 0xbfb8aa3b, v10
	v_mul_f32_e32 v11, 0xbfb8aa3b, v11
	v_add_f32_e32 v18, 1.0, v18
	v_add_f32_e32 v19, 1.0, v19
	v_rcp_f32_e32 v18, v18
	v_rcp_f32_e32 v19, v19
	v_exp_f32_e32 v10, v10
	v_exp_f32_e32 v11, v11
	v_mul_f32_e32 v6, 0xbfb8aa3b, v6
	v_mul_f32_e32 v7, 0xbfb8aa3b, v7
	v_add_f32_e32 v10, 1.0, v10
	v_add_f32_e32 v11, 1.0, v11
	v_rcp_f32_e32 v10, v10
	v_rcp_f32_e32 v11, v11
	v_exp_f32_e32 v6, v6
	v_exp_f32_e32 v7, v7
	v_mul_f32_e32 v0, 0xbfb8aa3b, v0
	v_mul_f32_e32 v1, 0xbfb8aa3b, v1
	v_add_f32_e32 v6, 1.0, v6
	v_add_f32_e32 v7, 1.0, v7
	v_rcp_f32_e32 v6, v6
	v_rcp_f32_e32 v7, v7
	v_exp_f32_e32 v0, v0
	v_exp_f32_e32 v1, v1
	s_mov_b64 s[76:77], -1
	s_andn2_b64 vcc, exec, s[4:5]
	v_add_f32_e32 v0, 1.0, v0
	v_add_f32_e32 v1, 1.0, v1
	v_rcp_f32_e32 v0, v0
	v_rcp_f32_e32 v1, v1
	s_nop 0
	v_lshlrev_b32_e32 v126, 16, v118
	v_and_b32_e32 v127, 0xffff0000, v118
	v_pk_mul_f32 v[114:115], v[114:115], v[126:127]
	v_lshlrev_b32_e32 v118, 16, v119
	v_cvt_pk_bf16_f32 v114, v114, v115
	v_mul_f32_e32 v115, 0xbfb8aa3b, v116
	v_exp_f32_e32 v115, v115
	v_and_b32_e32 v119, 0xffff0000, v119
	v_add_f32_e32 v115, 1.0, v115
	v_rcp_f32_e32 v116, v115
	v_mul_f32_e32 v115, 0xbfb8aa3b, v117
	v_exp_f32_e32 v115, v115
	s_nop 0
	v_add_f32_e32 v115, 1.0, v115
	v_rcp_f32_e32 v117, v115
	s_nop 0
	v_pk_mul_f32 v[116:117], v[116:117], v[118:119]
	s_nop 0
	v_cvt_pk_bf16_f32 v115, v116, v117
	v_lshlrev_b32_e32 v116, 16, v120
	v_and_b32_e32 v117, 0xffff0000, v120
	v_pk_mul_f32 v[110:111], v[110:111], v[116:117]
	s_nop 0
	v_cvt_pk_bf16_f32 v116, v110, v111
	v_mul_f32_e32 v110, 0xbfb8aa3b, v112
	v_mul_f32_e32 v111, 0xbfb8aa3b, v113
	v_exp_f32_e32 v110, v110
	v_exp_f32_e32 v111, v111
	v_lshlrev_b32_e32 v112, 16, v121
	v_and_b32_e32 v113, 0xffff0000, v121
	v_add_f32_e32 v110, 1.0, v110
	v_add_f32_e32 v111, 1.0, v111
	v_rcp_f32_e32 v110, v110
	v_rcp_f32_e32 v111, v111
	s_nop 0
	v_pk_mul_f32 v[110:111], v[110:111], v[112:113]
	s_nop 0
	v_cvt_pk_bf16_f32 v117, v110, v111
	v_lshlrev_b64 v[110:111], 12, v[122:123]
	v_lshl_add_u64 v[110:111], s[6:7], 0, v[110:111]
	v_lshl_add_u64 v[118:119], v[110:111], 0, v[146:147]
	s_nop 1
	v_mov_b32_e32 v110, v180
	v_mov_b32_e32 v111, v181
	v_mov_b32_e32 v112, v182
	v_mov_b32_e32 v113, v183
	s_nop 0
	global_store_dwordx4 v[118:119], v[114:117], off
	s_nop 0
	s_nop 0
	v_lshlrev_b32_e32 v114, 16, v110
	v_and_b32_e32 v115, 0xffff0000, v110
	v_pk_mul_f32 v[106:107], v[106:107], v[114:115]
	v_lshlrev_b32_e32 v110, 16, v111
	v_cvt_pk_bf16_f32 v106, v106, v107
	v_mul_f32_e32 v107, 0xbfb8aa3b, v108
	v_exp_f32_e32 v107, v107
	v_and_b32_e32 v111, 0xffff0000, v111
	v_add_f32_e32 v107, 1.0, v107
	v_rcp_f32_e32 v108, v107
	v_mul_f32_e32 v107, 0xbfb8aa3b, v109
	v_exp_f32_e32 v107, v107
	s_nop 0
	v_add_f32_e32 v107, 1.0, v107
	v_rcp_f32_e32 v109, v107
	s_nop 0
	v_pk_mul_f32 v[108:109], v[108:109], v[110:111]
	s_nop 0
	v_cvt_pk_bf16_f32 v107, v108, v109
	v_lshlrev_b32_e32 v108, 16, v112
	v_and_b32_e32 v109, 0xffff0000, v112
	v_pk_mul_f32 v[102:103], v[102:103], v[108:109]
	s_nop 0
	v_cvt_pk_bf16_f32 v108, v102, v103
	v_mul_f32_e32 v102, 0xbfb8aa3b, v104
	v_mul_f32_e32 v103, 0xbfb8aa3b, v105
	v_exp_f32_e32 v102, v102
	v_exp_f32_e32 v103, v103
	v_lshlrev_b32_e32 v104, 16, v113
	v_and_b32_e32 v105, 0xffff0000, v113
	v_add_f32_e32 v102, 1.0, v102
	v_add_f32_e32 v103, 1.0, v103
	v_rcp_f32_e32 v102, v102
	v_rcp_f32_e32 v103, v103
	s_nop 0
	v_pk_mul_f32 v[102:103], v[102:103], v[104:105]
	s_nop 0
	v_cvt_pk_bf16_f32 v109, v102, v103
	v_or_b32_e32 v102, 32, v148
	v_ashrrev_i32_e32 v103, 31, v102
	v_lshlrev_b64 v[104:105], 11, v[102:103]
	v_lshl_add_u64 v[104:105], s[10:11], 0, v[104:105]
	v_lshl_add_u64 v[104:105], v[104:105], 0, v[146:147]
	global_store_dwordx4 v[118:119], v[106:109], off offset:256
	s_nop 1
	v_mov_b32_e32 v106, v184
	v_mov_b32_e32 v107, v185
	v_mov_b32_e32 v108, v186
	v_mov_b32_e32 v109, v187
	s_nop 0
	v_lshlrev_b32_e32 v110, 16, v106
	v_and_b32_e32 v111, 0xffff0000, v106
	v_pk_mul_f32 v[98:99], v[98:99], v[110:111]
	v_lshlrev_b32_e32 v106, 16, v107
	v_cvt_pk_bf16_f32 v98, v98, v99
	v_mul_f32_e32 v99, 0xbfb8aa3b, v100
	v_exp_f32_e32 v99, v99
	v_and_b32_e32 v107, 0xffff0000, v107
	v_add_f32_e32 v99, 1.0, v99
	v_rcp_f32_e32 v100, v99
	v_mul_f32_e32 v99, 0xbfb8aa3b, v101
	v_exp_f32_e32 v99, v99
	s_nop 0
	v_add_f32_e32 v99, 1.0, v99
	v_rcp_f32_e32 v101, v99
	s_nop 0
	v_pk_mul_f32 v[100:101], v[100:101], v[106:107]
	s_nop 0
	v_cvt_pk_bf16_f32 v99, v100, v101
	v_lshlrev_b32_e32 v100, 16, v108
	v_and_b32_e32 v101, 0xffff0000, v108
	v_pk_mul_f32 v[94:95], v[94:95], v[100:101]
	s_nop 0
	v_cvt_pk_bf16_f32 v100, v94, v95
	v_mul_f32_e32 v94, 0xbfb8aa3b, v96
	v_mul_f32_e32 v95, 0xbfb8aa3b, v97
	v_exp_f32_e32 v94, v94
	v_exp_f32_e32 v95, v95
	v_lshlrev_b32_e32 v96, 16, v109
	v_and_b32_e32 v97, 0xffff0000, v109
	v_add_f32_e32 v94, 1.0, v94
	v_add_f32_e32 v95, 1.0, v95
	v_rcp_f32_e32 v94, v94
	v_rcp_f32_e32 v95, v95
	s_nop 0
	v_pk_mul_f32 v[94:95], v[94:95], v[96:97]
	s_nop 0
	v_cvt_pk_bf16_f32 v101, v94, v95
	v_lshlrev_b64 v[94:95], 12, v[102:103]
	v_lshl_add_u64 v[94:95], s[6:7], 0, v[94:95]
	v_lshl_add_u64 v[94:95], v[94:95], 0, v[146:147]
	global_store_dwordx4 v[94:95], v[98:101], off
	s_nop 1
	v_mov_b32_e32 v96, v188
	v_mov_b32_e32 v97, v189
	v_mov_b32_e32 v98, v190
	v_mov_b32_e32 v99, v191
	s_nop 0
	v_lshlrev_b32_e32 v100, 16, v96
	v_and_b32_e32 v101, 0xffff0000, v96
	v_pk_mul_f32 v[90:91], v[90:91], v[100:101]
	v_lshlrev_b32_e32 v96, 16, v97
	v_cvt_pk_bf16_f32 v90, v90, v91
	v_mul_f32_e32 v91, 0xbfb8aa3b, v92
	v_exp_f32_e32 v91, v91
	v_and_b32_e32 v97, 0xffff0000, v97
	v_add_f32_e32 v91, 1.0, v91
	v_rcp_f32_e32 v92, v91
	v_mul_f32_e32 v91, 0xbfb8aa3b, v93
	v_exp_f32_e32 v91, v91
	s_nop 0
	v_add_f32_e32 v91, 1.0, v91
	v_rcp_f32_e32 v93, v91
	s_nop 0
	v_pk_mul_f32 v[92:93], v[92:93], v[96:97]
	s_nop 0
	v_cvt_pk_bf16_f32 v91, v92, v93
	v_lshlrev_b32_e32 v92, 16, v98
	v_and_b32_e32 v93, 0xffff0000, v98
	v_pk_mul_f32 v[86:87], v[86:87], v[92:93]
	s_nop 0
	v_cvt_pk_bf16_f32 v92, v86, v87
	v_mul_f32_e32 v86, 0xbfb8aa3b, v88
	v_mul_f32_e32 v87, 0xbfb8aa3b, v89
	v_exp_f32_e32 v86, v86
	v_exp_f32_e32 v87, v87
	v_lshlrev_b32_e32 v88, 16, v99
	v_and_b32_e32 v89, 0xffff0000, v99
	v_add_f32_e32 v86, 1.0, v86
	v_add_f32_e32 v87, 1.0, v87
	v_rcp_f32_e32 v86, v86
	v_rcp_f32_e32 v87, v87
	s_nop 0
	v_pk_mul_f32 v[86:87], v[86:87], v[88:89]
	s_nop 0
	v_cvt_pk_bf16_f32 v93, v86, v87
	global_store_dwordx4 v[94:95], v[90:93], off offset:256
	s_nop 1
	v_or_b32_e32 v92, 48, v148
	v_ashrrev_i32_e32 v93, 31, v92
	v_lshlrev_b64 v[86:87], 11, v[92:93]
	v_lshl_add_u64 v[86:87], s[10:11], 0, v[86:87]
	v_lshl_add_u64 v[90:91], v[86:87], 0, v[146:147]
	s_nop 1
	v_mov_b32_e32 v86, v192
	v_mov_b32_e32 v87, v193
	v_mov_b32_e32 v88, v194
	v_mov_b32_e32 v89, v195
	s_nop 0
	v_lshlrev_b32_e32 v94, 16, v86
	v_and_b32_e32 v95, 0xffff0000, v86
	v_pk_mul_f32 v[82:83], v[82:83], v[94:95]
	v_lshlrev_b32_e32 v86, 16, v87
	v_cvt_pk_bf16_f32 v82, v82, v83
	v_mul_f32_e32 v83, 0xbfb8aa3b, v84
	v_exp_f32_e32 v83, v83
	v_and_b32_e32 v87, 0xffff0000, v87
	v_add_f32_e32 v83, 1.0, v83
	v_rcp_f32_e32 v84, v83
	v_mul_f32_e32 v83, 0xbfb8aa3b, v85
	v_exp_f32_e32 v83, v83
	s_nop 0
	v_add_f32_e32 v83, 1.0, v83
	v_rcp_f32_e32 v85, v83
	s_nop 0
	v_pk_mul_f32 v[84:85], v[84:85], v[86:87]
	s_nop 0
	v_cvt_pk_bf16_f32 v83, v84, v85
	v_lshlrev_b32_e32 v84, 16, v88
	v_and_b32_e32 v85, 0xffff0000, v88
	v_pk_mul_f32 v[78:79], v[78:79], v[84:85]
	s_nop 0
	v_cvt_pk_bf16_f32 v84, v78, v79
	v_mul_f32_e32 v78, 0xbfb8aa3b, v80
	v_mul_f32_e32 v79, 0xbfb8aa3b, v81
	v_exp_f32_e32 v78, v78
	v_exp_f32_e32 v79, v79
	v_lshlrev_b32_e32 v80, 16, v89
	v_and_b32_e32 v81, 0xffff0000, v89
	v_add_f32_e32 v78, 1.0, v78
	v_add_f32_e32 v79, 1.0, v79
	v_rcp_f32_e32 v78, v78
	v_rcp_f32_e32 v79, v79
	s_nop 0
	v_pk_mul_f32 v[78:79], v[78:79], v[80:81]
	s_nop 0
	v_cvt_pk_bf16_f32 v85, v78, v79
	v_lshlrev_b64 v[78:79], 12, v[92:93]
	v_lshl_add_u64 v[78:79], s[6:7], 0, v[78:79]
	v_lshl_add_u64 v[86:87], v[78:79], 0, v[146:147]
	s_nop 1
	v_mov_b32_e32 v78, v196
	v_mov_b32_e32 v79, v197
	v_mov_b32_e32 v80, v198
	v_mov_b32_e32 v81, v199
	s_nop 0
	global_store_dwordx4 v[86:87], v[82:85], off
	s_nop 0
	s_nop 0
	v_lshlrev_b32_e32 v82, 16, v78
	v_and_b32_e32 v83, 0xffff0000, v78
	v_pk_mul_f32 v[74:75], v[74:75], v[82:83]
	v_lshlrev_b32_e32 v78, 16, v79
	v_cvt_pk_bf16_f32 v74, v74, v75
	v_mul_f32_e32 v75, 0xbfb8aa3b, v76
	v_exp_f32_e32 v75, v75
	v_and_b32_e32 v79, 0xffff0000, v79
	v_add_f32_e32 v75, 1.0, v75
	v_rcp_f32_e32 v76, v75
	v_mul_f32_e32 v75, 0xbfb8aa3b, v77
	v_exp_f32_e32 v75, v75
	s_nop 0
	v_add_f32_e32 v75, 1.0, v75
	v_rcp_f32_e32 v77, v75
	s_nop 0
	v_pk_mul_f32 v[76:77], v[76:77], v[78:79]
	s_nop 0
	v_cvt_pk_bf16_f32 v75, v76, v77
	v_lshlrev_b32_e32 v76, 16, v80
	v_and_b32_e32 v77, 0xffff0000, v80
	v_pk_mul_f32 v[70:71], v[70:71], v[76:77]
	s_nop 0
	v_cvt_pk_bf16_f32 v76, v70, v71
	v_mul_f32_e32 v70, 0xbfb8aa3b, v72
	v_mul_f32_e32 v71, 0xbfb8aa3b, v73
	v_exp_f32_e32 v70, v70
	v_exp_f32_e32 v71, v71
	v_lshlrev_b32_e32 v72, 16, v81
	v_and_b32_e32 v73, 0xffff0000, v81
	v_add_f32_e32 v70, 1.0, v70
	v_add_f32_e32 v71, 1.0, v71
	v_rcp_f32_e32 v70, v70
	v_rcp_f32_e32 v71, v71
	s_nop 0
	v_pk_mul_f32 v[70:71], v[70:71], v[72:73]
	v_add_u32_e32 v72, 0x80, v148
	v_ashrrev_i32_e32 v73, 31, v72
	v_cvt_pk_bf16_f32 v77, v70, v71
	v_lshlrev_b64 v[70:71], 11, v[72:73]
	v_lshl_add_u64 v[70:71], s[10:11], 0, v[70:71]
	v_lshl_add_u64 v[70:71], v[70:71], 0, v[146:147]
	global_store_dwordx4 v[86:87], v[74:77], off offset:256
	s_nop 1
	v_mov_b32_e32 v74, v200
	v_mov_b32_e32 v75, v201
	v_mov_b32_e32 v76, v202
	v_mov_b32_e32 v77, v203
	s_nop 0
	v_lshlrev_b32_e32 v78, 16, v74
	v_and_b32_e32 v79, 0xffff0000, v74
	v_pk_mul_f32 v[66:67], v[66:67], v[78:79]
	v_lshlrev_b32_e32 v74, 16, v75
	v_cvt_pk_bf16_f32 v66, v66, v67
	v_mul_f32_e32 v67, 0xbfb8aa3b, v68
	v_exp_f32_e32 v67, v67
	v_and_b32_e32 v75, 0xffff0000, v75
	v_add_f32_e32 v67, 1.0, v67
	v_rcp_f32_e32 v68, v67
	v_mul_f32_e32 v67, 0xbfb8aa3b, v69
	v_exp_f32_e32 v67, v67
	s_nop 0
	v_add_f32_e32 v67, 1.0, v67
	v_rcp_f32_e32 v69, v67
	s_nop 0
	v_pk_mul_f32 v[68:69], v[68:69], v[74:75]
	s_nop 0
	v_cvt_pk_bf16_f32 v67, v68, v69
	v_lshlrev_b32_e32 v68, 16, v76
	v_and_b32_e32 v69, 0xffff0000, v76
	v_pk_mul_f32 v[62:63], v[62:63], v[68:69]
	s_nop 0
	v_cvt_pk_bf16_f32 v68, v62, v63
	v_mul_f32_e32 v62, 0xbfb8aa3b, v64
	v_mul_f32_e32 v63, 0xbfb8aa3b, v65
	v_exp_f32_e32 v62, v62
	v_exp_f32_e32 v63, v63
	v_lshlrev_b32_e32 v64, 16, v77
	v_and_b32_e32 v65, 0xffff0000, v77
	v_add_f32_e32 v62, 1.0, v62
	v_add_f32_e32 v63, 1.0, v63
	v_rcp_f32_e32 v62, v62
	v_rcp_f32_e32 v63, v63
	s_nop 0
	v_pk_mul_f32 v[62:63], v[62:63], v[64:65]
	s_nop 0
	v_cvt_pk_bf16_f32 v69, v62, v63
	v_lshlrev_b64 v[62:63], 12, v[72:73]
	v_lshl_add_u64 v[62:63], s[6:7], 0, v[62:63]
	v_lshl_add_u64 v[62:63], v[62:63], 0, v[146:147]
	global_store_dwordx4 v[62:63], v[66:69], off
	s_nop 1
	v_mov_b32_e32 v64, v204
	v_mov_b32_e32 v65, v205
	v_mov_b32_e32 v66, v206
	v_mov_b32_e32 v67, v207
	s_nop 0
	v_lshlrev_b32_e32 v68, 16, v64
	v_and_b32_e32 v69, 0xffff0000, v64
	v_pk_mul_f32 v[58:59], v[58:59], v[68:69]
	v_lshlrev_b32_e32 v64, 16, v65
	v_cvt_pk_bf16_f32 v58, v58, v59
	v_mul_f32_e32 v59, 0xbfb8aa3b, v60
	v_exp_f32_e32 v59, v59
	v_and_b32_e32 v65, 0xffff0000, v65
	v_add_f32_e32 v59, 1.0, v59
	v_rcp_f32_e32 v60, v59
	v_mul_f32_e32 v59, 0xbfb8aa3b, v61
	v_exp_f32_e32 v59, v59
	s_nop 0
	v_add_f32_e32 v59, 1.0, v59
	v_rcp_f32_e32 v61, v59
	s_nop 0
	v_pk_mul_f32 v[60:61], v[60:61], v[64:65]
	s_nop 0
	v_cvt_pk_bf16_f32 v59, v60, v61
	v_lshlrev_b32_e32 v60, 16, v66
	v_and_b32_e32 v61, 0xffff0000, v66
	v_pk_mul_f32 v[54:55], v[54:55], v[60:61]
	s_nop 0
	v_cvt_pk_bf16_f32 v60, v54, v55
	v_mul_f32_e32 v54, 0xbfb8aa3b, v56
	v_mul_f32_e32 v55, 0xbfb8aa3b, v57
	v_exp_f32_e32 v54, v54
	v_exp_f32_e32 v55, v55
	v_lshlrev_b32_e32 v56, 16, v67
	v_and_b32_e32 v57, 0xffff0000, v67
	v_add_f32_e32 v54, 1.0, v54
	v_add_f32_e32 v55, 1.0, v55
	v_rcp_f32_e32 v54, v54
	v_rcp_f32_e32 v55, v55
	s_nop 0
	v_pk_mul_f32 v[54:55], v[54:55], v[56:57]
	s_nop 0
	v_cvt_pk_bf16_f32 v61, v54, v55
	global_store_dwordx4 v[62:63], v[58:61], off offset:256
	s_nop 1
	v_add_u32_e32 v60, 0x90, v148
	v_ashrrev_i32_e32 v61, 31, v60
	v_lshlrev_b64 v[54:55], 11, v[60:61]
	v_lshl_add_u64 v[54:55], s[10:11], 0, v[54:55]
	v_lshl_add_u64 v[54:55], v[54:55], 0, v[146:147]
	s_nop 1
	v_mov_b32_e32 v56, v208
	v_mov_b32_e32 v57, v209
	v_mov_b32_e32 v58, v210
	v_mov_b32_e32 v59, v211
	s_nop 0
	v_lshlrev_b32_e32 v62, 16, v56
	v_and_b32_e32 v63, 0xffff0000, v56
	v_pk_mul_f32 v[50:51], v[50:51], v[62:63]
	v_lshlrev_b32_e32 v56, 16, v57
	v_cvt_pk_bf16_f32 v50, v50, v51
	v_mul_f32_e32 v51, 0xbfb8aa3b, v52
	v_exp_f32_e32 v51, v51
	v_and_b32_e32 v57, 0xffff0000, v57
	v_add_f32_e32 v51, 1.0, v51
	v_rcp_f32_e32 v52, v51
	v_mul_f32_e32 v51, 0xbfb8aa3b, v53
	v_exp_f32_e32 v51, v51
	s_nop 0
	v_add_f32_e32 v51, 1.0, v51
	v_rcp_f32_e32 v53, v51
	s_nop 0
	v_pk_mul_f32 v[52:53], v[52:53], v[56:57]
	s_nop 0
	v_cvt_pk_bf16_f32 v51, v52, v53
	v_lshlrev_b32_e32 v52, 16, v58
	v_and_b32_e32 v53, 0xffff0000, v58
	v_pk_mul_f32 v[46:47], v[46:47], v[52:53]
	s_nop 0
	v_cvt_pk_bf16_f32 v52, v46, v47
	v_mul_f32_e32 v46, 0xbfb8aa3b, v48
	v_mul_f32_e32 v47, 0xbfb8aa3b, v49
	v_exp_f32_e32 v46, v46
	v_exp_f32_e32 v47, v47
	v_lshlrev_b32_e32 v48, 16, v59
	v_and_b32_e32 v49, 0xffff0000, v59
	v_add_f32_e32 v46, 1.0, v46
	v_add_f32_e32 v47, 1.0, v47
	v_rcp_f32_e32 v46, v46
	v_rcp_f32_e32 v47, v47
	s_nop 0
	v_pk_mul_f32 v[46:47], v[46:47], v[48:49]
	s_nop 0
	v_cvt_pk_bf16_f32 v53, v46, v47
	v_lshlrev_b64 v[46:47], 12, v[60:61]
	v_lshl_add_u64 v[46:47], s[6:7], 0, v[46:47]
	v_lshl_add_u64 v[46:47], v[46:47], 0, v[146:147]
	global_store_dwordx4 v[46:47], v[50:53], off
	s_nop 1
	v_mov_b32_e32 v48, v212
	v_mov_b32_e32 v49, v213
	v_mov_b32_e32 v50, v214
	v_mov_b32_e32 v51, v215
	s_nop 0
	v_lshlrev_b32_e32 v52, 16, v48
	v_and_b32_e32 v53, 0xffff0000, v48
	v_pk_mul_f32 v[42:43], v[42:43], v[52:53]
	v_lshlrev_b32_e32 v48, 16, v49
	v_cvt_pk_bf16_f32 v42, v42, v43
	v_mul_f32_e32 v43, 0xbfb8aa3b, v44
	v_exp_f32_e32 v43, v43
	v_and_b32_e32 v49, 0xffff0000, v49
	v_add_f32_e32 v43, 1.0, v43
	v_rcp_f32_e32 v44, v43
	v_mul_f32_e32 v43, 0xbfb8aa3b, v45
	v_exp_f32_e32 v43, v43
	s_nop 0
	v_add_f32_e32 v43, 1.0, v43
	v_rcp_f32_e32 v45, v43
	s_nop 0
	v_pk_mul_f32 v[44:45], v[44:45], v[48:49]
	s_nop 0
	v_cvt_pk_bf16_f32 v43, v44, v45
	v_lshlrev_b32_e32 v44, 16, v50
	v_and_b32_e32 v45, 0xffff0000, v50
	v_pk_mul_f32 v[38:39], v[38:39], v[44:45]
	s_nop 0
	v_cvt_pk_bf16_f32 v44, v38, v39
	v_mul_f32_e32 v38, 0xbfb8aa3b, v40
	v_mul_f32_e32 v39, 0xbfb8aa3b, v41
	v_exp_f32_e32 v38, v38
	v_exp_f32_e32 v39, v39
	v_lshlrev_b32_e32 v40, 16, v51
	v_and_b32_e32 v41, 0xffff0000, v51
	v_add_f32_e32 v38, 1.0, v38
	v_add_f32_e32 v39, 1.0, v39
	v_rcp_f32_e32 v38, v38
	v_rcp_f32_e32 v39, v39
	s_nop 0
	v_pk_mul_f32 v[38:39], v[38:39], v[40:41]
	s_nop 0
	v_cvt_pk_bf16_f32 v45, v38, v39
	global_store_dwordx4 v[46:47], v[42:45], off offset:256
	s_nop 1
	v_add_u32_e32 v44, 0xa0, v148
	v_ashrrev_i32_e32 v45, 31, v44
	v_lshlrev_b64 v[38:39], 11, v[44:45]
	v_lshl_add_u64 v[38:39], s[10:11], 0, v[38:39]
	v_lshl_add_u64 v[38:39], v[38:39], 0, v[146:147]
	s_nop 1
	v_mov_b32_e32 v40, v216
	v_mov_b32_e32 v41, v217
	v_mov_b32_e32 v42, v218
	v_mov_b32_e32 v43, v219
	s_nop 0
	v_lshlrev_b32_e32 v46, 16, v40
	v_and_b32_e32 v47, 0xffff0000, v40
	v_pk_mul_f32 v[34:35], v[34:35], v[46:47]
	v_lshlrev_b32_e32 v40, 16, v41
	v_cvt_pk_bf16_f32 v34, v34, v35
	v_mul_f32_e32 v35, 0xbfb8aa3b, v36
	v_exp_f32_e32 v35, v35
	v_and_b32_e32 v41, 0xffff0000, v41
	v_add_f32_e32 v35, 1.0, v35
	v_rcp_f32_e32 v36, v35
	v_mul_f32_e32 v35, 0xbfb8aa3b, v37
	v_exp_f32_e32 v35, v35
	s_nop 0
	v_add_f32_e32 v35, 1.0, v35
	v_rcp_f32_e32 v37, v35
	s_nop 0
	v_pk_mul_f32 v[36:37], v[36:37], v[40:41]
	s_nop 0
	v_cvt_pk_bf16_f32 v35, v36, v37
	v_lshlrev_b32_e32 v36, 16, v42
	v_and_b32_e32 v37, 0xffff0000, v42
	v_pk_mul_f32 v[30:31], v[30:31], v[36:37]
	s_nop 0
	v_cvt_pk_bf16_f32 v36, v30, v31
	v_mul_f32_e32 v30, 0xbfb8aa3b, v32
	v_mul_f32_e32 v31, 0xbfb8aa3b, v33
	v_exp_f32_e32 v30, v30
	v_exp_f32_e32 v31, v31
	v_lshlrev_b32_e32 v32, 16, v43
	v_and_b32_e32 v33, 0xffff0000, v43
	v_add_f32_e32 v30, 1.0, v30
	v_add_f32_e32 v31, 1.0, v31
	v_rcp_f32_e32 v30, v30
	v_rcp_f32_e32 v31, v31
	s_nop 0
	v_pk_mul_f32 v[30:31], v[30:31], v[32:33]
	s_nop 0
	v_cvt_pk_bf16_f32 v37, v30, v31
	v_lshlrev_b64 v[30:31], 12, v[44:45]
	v_lshl_add_u64 v[30:31], s[6:7], 0, v[30:31]
	v_lshl_add_u64 v[30:31], v[30:31], 0, v[146:147]
	global_store_dwordx4 v[30:31], v[34:37], off
	s_nop 1
	v_mov_b32_e32 v32, v220
	v_mov_b32_e32 v33, v221
	v_mov_b32_e32 v34, v222
	v_mov_b32_e32 v35, v223
	s_nop 0
	v_lshlrev_b32_e32 v36, 16, v32
	v_and_b32_e32 v37, 0xffff0000, v32
	v_pk_mul_f32 v[26:27], v[26:27], v[36:37]
	v_lshlrev_b32_e32 v32, 16, v33
	v_cvt_pk_bf16_f32 v26, v26, v27
	v_mul_f32_e32 v27, 0xbfb8aa3b, v28
	v_exp_f32_e32 v27, v27
	v_and_b32_e32 v33, 0xffff0000, v33
	v_add_f32_e32 v27, 1.0, v27
	v_rcp_f32_e32 v28, v27
	v_mul_f32_e32 v27, 0xbfb8aa3b, v29
	v_exp_f32_e32 v27, v27
	s_nop 0
	v_add_f32_e32 v27, 1.0, v27
	v_rcp_f32_e32 v29, v27
	s_nop 0
	v_pk_mul_f32 v[28:29], v[28:29], v[32:33]
	s_nop 0
	v_cvt_pk_bf16_f32 v27, v28, v29
	v_lshlrev_b32_e32 v28, 16, v34
	v_and_b32_e32 v29, 0xffff0000, v34
	v_pk_mul_f32 v[22:23], v[22:23], v[28:29]
	s_nop 0
	v_cvt_pk_bf16_f32 v28, v22, v23
	v_mul_f32_e32 v22, 0xbfb8aa3b, v24
	v_mul_f32_e32 v23, 0xbfb8aa3b, v25
	v_exp_f32_e32 v22, v22
	v_exp_f32_e32 v23, v23
	v_lshlrev_b32_e32 v24, 16, v35
	v_and_b32_e32 v25, 0xffff0000, v35
	v_add_f32_e32 v22, 1.0, v22
	v_add_f32_e32 v23, 1.0, v23
	v_rcp_f32_e32 v22, v22
	v_rcp_f32_e32 v23, v23
	s_nop 0
	v_pk_mul_f32 v[22:23], v[22:23], v[24:25]
	s_nop 0
	v_cvt_pk_bf16_f32 v29, v22, v23
	global_store_dwordx4 v[30:31], v[26:29], off offset:256
	s_nop 1
	v_add_u32_e32 v28, 0xb0, v148
	v_ashrrev_i32_e32 v29, 31, v28
	v_lshlrev_b64 v[22:23], 11, v[28:29]
	v_lshl_add_u64 v[22:23], s[10:11], 0, v[22:23]
	v_lshl_add_u64 v[22:23], v[22:23], 0, v[146:147]
	s_nop 1
	v_mov_b32_e32 v24, v224
	v_mov_b32_e32 v25, v225
	v_mov_b32_e32 v26, v226
	v_mov_b32_e32 v27, v227
	s_nop 0
	v_lshlrev_b32_e32 v30, 16, v24
	v_and_b32_e32 v31, 0xffff0000, v24
	v_pk_mul_f32 v[18:19], v[18:19], v[30:31]
	s_nop 0
	v_cvt_pk_bf16_f32 v24, v18, v19
	v_mul_f32_e32 v18, 0xbfb8aa3b, v20
	v_mul_f32_e32 v19, 0xbfb8aa3b, v21
	v_exp_f32_e32 v18, v18
	v_exp_f32_e32 v19, v19
	v_lshlrev_b32_e32 v20, 16, v25
	v_and_b32_e32 v21, 0xffff0000, v25
	v_add_f32_e32 v18, 1.0, v18
	v_add_f32_e32 v19, 1.0, v19
	v_rcp_f32_e32 v18, v18
	v_rcp_f32_e32 v19, v19
	s_nop 0
	v_pk_mul_f32 v[18:19], v[18:19], v[20:21]
	s_nop 0
	v_cvt_pk_bf16_f32 v25, v18, v19
	v_lshlrev_b32_e32 v18, 16, v26
	v_and_b32_e32 v19, 0xffff0000, v26
	v_pk_mul_f32 v[10:11], v[10:11], v[18:19]
	s_nop 0
	v_cvt_pk_bf16_f32 v26, v10, v11
	v_mul_f32_e32 v10, 0xbfb8aa3b, v12
	v_mul_f32_e32 v11, 0xbfb8aa3b, v13
	v_exp_f32_e32 v10, v10
	v_exp_f32_e32 v11, v11
	v_lshlrev_b32_e32 v12, 16, v27
	v_and_b32_e32 v13, 0xffff0000, v27
	v_add_f32_e32 v10, 1.0, v10
	v_add_f32_e32 v11, 1.0, v11
	v_rcp_f32_e32 v10, v10
	v_rcp_f32_e32 v11, v11
	s_nop 0
	v_pk_mul_f32 v[10:11], v[10:11], v[12:13]
	s_nop 0
	v_cvt_pk_bf16_f32 v27, v10, v11
	v_lshlrev_b64 v[10:11], 12, v[28:29]
	v_lshl_add_u64 v[10:11], s[6:7], 0, v[10:11]
	v_lshl_add_u64 v[18:19], v[10:11], 0, v[146:147]
	s_nop 1
	v_mov_b32_e32 v10, v228
	v_mov_b32_e32 v11, v229
	v_mov_b32_e32 v12, v230
	v_mov_b32_e32 v13, v231
	s_nop 0
	v_lshlrev_b32_e32 v20, 16, v10
	v_and_b32_e32 v21, 0xffff0000, v10
	v_pk_mul_f32 v[6:7], v[6:7], v[20:21]
	v_lshlrev_b32_e32 v10, 16, v11
	v_cvt_pk_bf16_f32 v6, v6, v7
	v_mul_f32_e32 v7, 0xbfb8aa3b, v8
	v_exp_f32_e32 v7, v7
	v_and_b32_e32 v11, 0xffff0000, v11
	global_store_dwordx4 v[18:19], v[24:27], off
	v_add_f32_e32 v7, 1.0, v7
	v_rcp_f32_e32 v8, v7
	v_mul_f32_e32 v7, 0xbfb8aa3b, v9
	v_exp_f32_e32 v7, v7
	s_nop 0
	v_add_f32_e32 v7, 1.0, v7
	v_rcp_f32_e32 v9, v7
	s_nop 0
	v_pk_mul_f32 v[8:9], v[8:9], v[10:11]
	s_nop 0
	v_cvt_pk_bf16_f32 v7, v8, v9
	v_lshlrev_b32_e32 v8, 16, v12
	v_and_b32_e32 v9, 0xffff0000, v12
	v_pk_mul_f32 v[0:1], v[0:1], v[8:9]
	s_nop 0
	v_cvt_pk_bf16_f32 v8, v0, v1
	v_mul_f32_e32 v0, 0xbfb8aa3b, v2
	v_mul_f32_e32 v1, 0xbfb8aa3b, v3
	v_exp_f32_e32 v0, v0
	v_exp_f32_e32 v1, v1
	v_lshlrev_b32_e32 v2, 16, v13
	v_and_b32_e32 v3, 0xffff0000, v13
	v_add_f32_e32 v0, 1.0, v0
	v_add_f32_e32 v1, 1.0, v1
	v_rcp_f32_e32 v0, v0
	v_rcp_f32_e32 v1, v1
	s_nop 0
	v_pk_mul_f32 v[0:1], v[0:1], v[2:3]
	s_nop 0
	v_cvt_pk_bf16_f32 v9, v0, v1
	global_store_dwordx4 v[18:19], v[6:9], off offset:256
	s_cbranch_vccnz .LBB0_108
	s_andn2_b64 vcc, exec, s[12:13]
	s_cbranch_vccnz .LBB0_107
	s_barrier
	s_branch .LBB0_107

.LBB0_474:
	s_lshl_b32 s0, s12, 8
	s_waitcnt lgkmcnt(0)
	s_load_dwordx4 s[4:7], s[58:59], 0x18
	s_load_dwordx2 s[8:9], s[58:59], 0x28
	s_and_b32 s3, s0, 0x700
	v_or_b32_e32 v1, s3, v168
	v_lshlrev_b32_e32 v5, 2, v1
	s_waitcnt lgkmcnt(0)
	global_load_dword v12, v5, s[6:7]
	s_or_b32 s0, s0, 0xfffff800
	v_or_b32_e32 v0, s0, v168
	v_ashrrev_i32_e32 v1, 31, v0
	v_lshl_add_u64 v[6:7], v[0:1], 2, s[4:5]
	v_add_co_u32_e32 v2, vcc, s91, v6
	s_ashr_i32 s0, s0, 31
	s_nop 0
	v_addc_co_u32_e32 v3, vcc, 0, v7, vcc
	v_add_co_u32_e32 v8, vcc, s96, v6
	v_mov_b32_e32 v1, s0
	s_nop 0
	v_addc_co_u32_e32 v9, vcc, 0, v7, vcc
	v_add_co_u32_e32 v10, vcc, s97, v6
	v_lshl_add_u64 v[0:1], v[0:1], 2, s[4:5]
	s_nop 0
	v_addc_co_u32_e32 v11, vcc, 0, v7, vcc
	global_load_dword v20, v[2:3], off
	global_load_dword v21, v[8:9], off
	global_load_dword v22, v[10:11], off
	v_add_co_u32_e32 v2, vcc, s48, v6
	s_ashr_i32 s3, s12, 3
	s_nop 0
	v_addc_co_u32_e32 v3, vcc, 0, v7, vcc
	global_load_dword v3, v[2:3], off
	v_add_co_u32_e32 v8, vcc, s49, v6
	s_mul_hi_i32 s10, s3, 0x2aaaaaab
	s_nop 0
	v_addc_co_u32_e32 v9, vcc, 0, v7, vcc
	global_load_dword v24, v[8:9], off
	v_add_co_u32_e32 v8, vcc, s50, v6
	v_lshl_add_u32 v2, v168, 2, s34
	s_nop 0
	v_addc_co_u32_e32 v9, vcc, 0, v7, vcc
	global_load_dword v25, v[8:9], off
	v_add_co_u32_e32 v8, vcc, s51, v6
	s_lshr_b32 s11, s10, 31
	s_nop 0
	v_addc_co_u32_e32 v9, vcc, 0, v7, vcc
	v_add_co_u32_e32 v6, vcc, s94, v6
	global_load_dword v26, v[8:9], off
	s_nop 0
	v_addc_co_u32_e32 v7, vcc, 0, v7, vcc
	global_load_dword v27, v[6:7], off
	global_load_dword v28, v5, s[6:7] offset:256
	global_load_dword v29, v5, s[6:7] offset:512
	s_nop 0
	global_load_dword v5, v5, s[6:7] offset:768
	v_add_co_u32_e32 v6, vcc, s91, v0
	s_lshr_b32 s10, s10, 4
	s_nop 0
	v_addc_co_u32_e32 v7, vcc, 0, v1, vcc
	v_add_co_u32_e32 v8, vcc, s96, v0
	s_add_i32 s10, s10, s11
	s_nop 0
	v_addc_co_u32_e32 v9, vcc, 0, v1, vcc
	v_add_co_u32_e32 v10, vcc, s97, v0
	s_mulk_i32 s10, 0x60
	s_nop 0
	v_addc_co_u32_e32 v11, vcc, 0, v1, vcc
	global_load_dword v30, v[6:7], off offset:256
	global_load_dword v31, v[8:9], off offset:256
	global_load_dword v32, v[10:11], off offset:256
	s_mul_hi_i32 s0, s12, 0x2aaaaaab
	s_sub_i32 s3, s3, s10
	s_lshr_b32 s4, s0, 31
	s_ashr_i32 s0, s0, 7
	s_add_i32 s0, s0, s4
	s_lshl_b32 s4, s3, 7
	s_and_b32 s7, s12, 7
	s_ashr_i32 s5, s4, 31
	s_mul_i32 s6, s0, 0x6000000
	s_mul_i32 s7, s7, 0xc00000
	s_mul_hi_i32 s3, s0, 0x6000000
	s_add_u32 s6, s6, s7
	s_addc_u32 s3, s3, 0
	s_lshl_b64 s[4:5], s[4:5], 2
	s_waitcnt vmcnt(0)
	v_mul_f32_e32 v13, 0xbfb8aa3b, v12
	v_exp_f32_e32 v13, v13
	s_add_u32 s7, s8, s4
	s_addc_u32 s8, s9, s5
	s_add_u32 s6, s7, s6
	v_add_f32_e32 v13, 1.0, v13
	v_rcp_f32_e32 v13, v13
	s_addc_u32 s7, s8, s3
	s_mov_b32 s3, -8
	global_load_dword v46, v[6:7], off offset:512
	global_load_dword v47, v[8:9], off offset:512
	v_mul_f32_e32 v35, v12, v13
	v_add_co_u32_e32 v12, vcc, s48, v0
	v_mul_f32_e32 v18, 0xbfb8aa3b, v20
	s_nop 0
	v_addc_co_u32_e32 v13, vcc, 0, v1, vcc
	global_load_dword v37, v[12:13], off offset:256
	v_exp_f32_e32 v18, v18
	v_mul_f32_e32 v19, 0xbfb8aa3b, v21
	v_exp_f32_e32 v19, v19
	v_mul_f32_e32 v23, 0xbfb8aa3b, v22
	v_add_f32_e32 v18, 1.0, v18
	v_mul_f32_e32 v36, 0xbfb8aa3b, v3
	v_rcp_f32_e32 v33, v18
	v_exp_f32_e32 v36, v36
	v_add_f32_e32 v19, 1.0, v19
	v_add_co_u32_e32 v18, vcc, s49, v0
	v_exp_f32_e32 v23, v23
	v_rcp_f32_e32 v34, v19
	v_addc_co_u32_e32 v19, vcc, 0, v1, vcc
	v_mul_f32_e32 v33, v20, v33
	v_add_f32_e32 v20, 1.0, v36
	v_mul_f32_e32 v42, 0xbfb8aa3b, v24
	global_load_dword v38, v[18:19], off offset:256
	v_rcp_f32_e32 v36, v20
	v_exp_f32_e32 v42, v42
	v_add_f32_e32 v23, 1.0, v23
	v_rcp_f32_e32 v23, v23
	v_mul_f32_e32 v3, v3, v36
	v_add_f32_e32 v36, 1.0, v42
	v_mul_f32_e32 v42, 0xbfb8aa3b, v25
	v_exp_f32_e32 v42, v42
	v_add_co_u32_e32 v20, vcc, s50, v0
	v_mul_f32_e32 v34, v21, v34
	s_nop 0
	v_addc_co_u32_e32 v21, vcc, 0, v1, vcc
	v_mul_f32_e32 v39, v22, v23
	v_add_co_u32_e32 v22, vcc, s51, v0
	global_load_dword v40, v[20:21], off offset:256
	s_nop 0
	v_addc_co_u32_e32 v23, vcc, 0, v1, vcc
	v_add_f32_e32 v42, 1.0, v42
	global_load_dword v41, v[22:23], off offset:256
	v_rcp_f32_e32 v42, v42
	v_mul_f32_e32 v45, 0xbfb8aa3b, v27
	v_exp_f32_e32 v45, v45
	v_add_co_u32_e32 v0, vcc, s94, v0
	v_mul_f32_e32 v25, v25, v42
	s_nop 0
	v_addc_co_u32_e32 v1, vcc, 0, v1, vcc
	v_mul_f32_e32 v42, 0xbfb8aa3b, v28
	global_load_dword v43, v[0:1], off offset:256
	v_rcp_f32_e32 v36, v36
	v_add_f32_e32 v45, 1.0, v45
	v_exp_f32_e32 v42, v42
	v_rcp_f32_e32 v45, v45
	v_mul_f32_e32 v24, v24, v36
	global_load_dword v36, v[10:11], off offset:512
	s_nop 0
	global_load_dword v8, v[8:9], off offset:768
	s_nop 0
	global_load_dword v6, v[6:7], off offset:768
	v_mul_f32_e32 v7, 0xbfb8aa3b, v30
	v_add_f32_e32 v42, 1.0, v42
	v_mul_f32_e32 v27, v27, v45
	v_exp_f32_e32 v7, v7
	v_rcp_f32_e32 v42, v42
	v_mul_f32_e32 v45, 0xbfb8aa3b, v31
	v_exp_f32_e32 v45, v45
	v_mul_f32_e32 v44, 0xbfb8aa3b, v26
	v_exp_f32_e32 v44, v44
	v_add_f32_e32 v7, 1.0, v7
	v_mul_f32_e32 v28, v28, v42
	v_rcp_f32_e32 v7, v7
	ds_write2st64_b32 v2, v35, v28 offset1:1
	v_add_f32_e32 v28, 1.0, v45
	v_rcp_f32_e32 v28, v28
	v_add_f32_e32 v44, 1.0, v44
	v_rcp_f32_e32 v44, v44
	v_mul_f32_e32 v7, v30, v7
	ds_write2st64_b32 v2, v33, v7 offset0:4 offset1:5
	v_mul_f32_e32 v7, v31, v28
	v_mul_f32_e32 v35, 0xbfb8aa3b, v32
	ds_write2st64_b32 v2, v34, v7 offset0:8 offset1:9
	v_mul_f32_e32 v26, v26, v44
	global_load_dword v9, v[12:13], off offset:512
	global_load_dword v44, v[18:19], off offset:512
	global_load_dword v48, v[20:21], off offset:512
	global_load_dword v30, v[22:23], off offset:512
	global_load_dword v42, v[0:1], off offset:512
	v_exp_f32_e32 v35, v35
	global_load_dword v18, v[18:19], off offset:768
	s_nop 0
	global_load_dword v12, v[12:13], off offset:768
	s_nop 0
	global_load_dword v10, v[10:11], off offset:768
	s_waitcnt vmcnt(15)
	v_mul_f32_e32 v11, 0xbfb8aa3b, v37
	v_exp_f32_e32 v11, v11
	v_add_f32_e32 v7, 1.0, v35
	v_rcp_f32_e32 v7, v7
	v_add_f32_e32 v11, 1.0, v11
	v_rcp_f32_e32 v11, v11
	v_mul_f32_e32 v7, v32, v7
	ds_write2st64_b32 v2, v39, v7 offset0:12 offset1:13
	v_mul_f32_e32 v7, v37, v11
	ds_write2st64_b32 v2, v3, v7 offset0:16 offset1:17
	global_load_dword v0, v[0:1], off offset:768
	s_nop 0
	global_load_dword v1, v[22:23], off offset:768
	global_load_dword v11, v[20:21], off offset:768
	s_waitcnt vmcnt(17)
	v_mul_f32_e32 v13, 0xbfb8aa3b, v38
	v_exp_f32_e32 v13, v13
	s_waitcnt vmcnt(16)
	v_mul_f32_e32 v7, 0xbfb8aa3b, v40
	v_add_f32_e32 v13, 1.0, v13
	v_rcp_f32_e32 v13, v13
	v_exp_f32_e32 v7, v7
	v_mul_f32_e32 v3, v38, v13
	s_waitcnt vmcnt(15)
	v_mul_f32_e32 v13, 0xbfb8aa3b, v41
	v_exp_f32_e32 v13, v13
	ds_write2st64_b32 v2, v24, v3 offset0:20 offset1:21
	v_add_f32_e32 v3, 1.0, v7
	v_rcp_f32_e32 v3, v3
	v_add_f32_e32 v7, 1.0, v13
	v_rcp_f32_e32 v7, v7
	s_waitcnt vmcnt(14)
	v_mul_f32_e32 v13, 0xbfb8aa3b, v43
	v_exp_f32_e32 v13, v13
	v_mul_f32_e32 v24, 0xbfb8aa3b, v5
	v_mul_f32_e32 v3, v40, v3
	v_exp_f32_e32 v24, v24
	ds_write2st64_b32 v2, v25, v3 offset0:24 offset1:25
	v_mul_f32_e32 v3, v41, v7
	v_add_f32_e32 v7, 1.0, v13
	v_rcp_f32_e32 v7, v7
	v_mul_f32_e32 v13, 0xbfb8aa3b, v29
	v_exp_f32_e32 v13, v13
	v_add_f32_e32 v24, 1.0, v24
	s_waitcnt vmcnt(11)
	v_mul_f32_e32 v25, 0xbfb8aa3b, v6
	v_rcp_f32_e32 v24, v24
	v_exp_f32_e32 v25, v25
	ds_write2st64_b32 v2, v26, v3 offset0:28 offset1:29
	v_mul_f32_e32 v3, v43, v7
	v_mul_f32_e32 v7, 0xbfb8aa3b, v46
	ds_write2st64_b32 v2, v27, v3 offset0:32 offset1:33
	v_add_f32_e32 v3, 1.0, v13
	v_exp_f32_e32 v7, v7
	v_mul_f32_e32 v13, 0xbfb8aa3b, v47
	v_mul_f32_e32 v26, 0xbfb8aa3b, v8
	v_exp_f32_e32 v13, v13
	v_rcp_f32_e32 v3, v3
	v_exp_f32_e32 v26, v26
	v_mul_f32_e32 v5, v5, v24
	v_add_f32_e32 v24, 1.0, v25
	v_rcp_f32_e32 v24, v24
	v_add_f32_e32 v7, 1.0, v7
	v_rcp_f32_e32 v7, v7
	v_add_f32_e32 v13, 1.0, v13
	v_mul_f32_e32 v3, v29, v3
	v_add_f32_e32 v25, 1.0, v26
	v_rcp_f32_e32 v13, v13
	v_mul_f32_e32 v19, 0xbfb8aa3b, v36
	v_rcp_f32_e32 v25, v25
	ds_write2st64_b32 v2, v3, v5 offset0:2 offset1:3
	s_waitcnt vmcnt(3)
	v_mul_f32_e32 v5, 0xbfb8aa3b, v10
	v_exp_f32_e32 v19, v19
	v_mul_f32_e32 v3, v6, v24
	v_exp_f32_e32 v5, v5
	v_mul_f32_e32 v6, 0xbfb8aa3b, v12
	v_exp_f32_e32 v6, v6
	v_mul_f32_e32 v7, v46, v7
	v_mul_f32_e32 v13, v47, v13
	ds_write2st64_b32 v2, v7, v3 offset0:6 offset1:7
	v_mul_f32_e32 v3, v8, v25
	v_add_f32_e32 v19, 1.0, v19
	v_mul_f32_e32 v20, 0xbfb8aa3b, v9
	ds_write2st64_b32 v2, v13, v3 offset0:10 offset1:11
	v_add_f32_e32 v3, 1.0, v5
	v_exp_f32_e32 v20, v20
	v_mul_f32_e32 v21, 0xbfb8aa3b, v44
	v_rcp_f32_e32 v19, v19
	v_rcp_f32_e32 v3, v3
	v_add_f32_e32 v5, 1.0, v6
	v_mul_f32_e32 v6, 0xbfb8aa3b, v18
	v_exp_f32_e32 v21, v21
	v_rcp_f32_e32 v5, v5
	v_exp_f32_e32 v6, v6
	v_add_f32_e32 v20, 1.0, v20
	v_mul_f32_e32 v19, v36, v19
	v_mul_f32_e32 v3, v10, v3
	v_rcp_f32_e32 v20, v20
	v_add_f32_e32 v21, 1.0, v21
	ds_write2st64_b32 v2, v19, v3 offset0:14 offset1:15
	v_mul_f32_e32 v3, v12, v5
	v_add_f32_e32 v5, 1.0, v6
	v_rcp_f32_e32 v21, v21
	v_mul_f32_e32 v22, 0xbfb8aa3b, v48
	v_rcp_f32_e32 v5, v5
	s_waitcnt vmcnt(0)
	v_mul_f32_e32 v6, 0xbfb8aa3b, v11
	v_exp_f32_e32 v22, v22
	v_exp_f32_e32 v6, v6
	v_mul_f32_e32 v9, v9, v20
	v_mul_f32_e32 v20, v44, v21
	ds_write2st64_b32 v2, v9, v3 offset0:18 offset1:19
	v_mul_f32_e32 v3, v18, v5
	v_add_f32_e32 v21, 1.0, v22
	v_mul_f32_e32 v22, 0xbfb8aa3b, v30
	v_mul_f32_e32 v23, 0xbfb8aa3b, v42
	ds_write2st64_b32 v2, v20, v3 offset0:22 offset1:23
	v_add_f32_e32 v3, 1.0, v6
	v_mul_f32_e32 v5, 0xbfb8aa3b, v1
	v_mul_f32_e32 v6, 0xbfb8aa3b, v0
	v_exp_f32_e32 v22, v22
	v_exp_f32_e32 v23, v23
	v_exp_f32_e32 v5, v5
	v_exp_f32_e32 v6, v6
	v_add_f32_e32 v22, 1.0, v22
	v_add_f32_e32 v23, 1.0, v23
	v_add_f32_e32 v5, 1.0, v5
	v_add_f32_e32 v6, 1.0, v6
	v_rcp_f32_e32 v21, v21
	v_rcp_f32_e32 v22, v22
	v_rcp_f32_e32 v23, v23
	v_rcp_f32_e32 v3, v3
	v_rcp_f32_e32 v5, v5
	v_rcp_f32_e32 v6, v6
	v_mul_f32_e32 v21, v48, v21
	v_mul_f32_e32 v22, v30, v22
	v_mul_f32_e32 v23, v42, v23
	v_mul_f32_e32 v3, v11, v3
	v_mul_f32_e32 v1, v1, v5
	v_mul_f32_e32 v0, v0, v6
	ds_write2st64_b32 v2, v21, v3 offset0:26 offset1:27
	ds_write2st64_b32 v2, v22, v1 offset0:30 offset1:31
	ds_write2st64_b32 v2, v23, v0 offset0:34 offset1:35
	s_waitcnt lgkmcnt(0)
	v_lshlrev_b32_e32 v0, 3, v168
	v_mov_b32_e32 v1, v4
	v_lshl_add_u64 v[2:3], s[6:7], 0, v[0:1]
	v_mov_b32_e32 v6, 0
	v_lshl_add_u64 v[2:3], v[2:3], 0, s[52:53]
	s_mov_b32 s6, s34
	v_mov_b32_e32 v7, v6
	v_mov_b32_e32 v8, v6
	v_mov_b32_e32 v9, v6
	v_mov_b32_e32 v10, v6
	v_mov_b32_e32 v11, v6
	v_mov_b32_e32 v12, v6
	v_mov_b32_e32 v13, v6
	v_mov_b32_e32 v18, v6
	v_mov_b32_e32 v19, v6
	v_mov_b32_e32 v20, v6
	v_mov_b32_e32 v21, v6
	v_mov_b32_e32 v22, v6
	v_mov_b32_e32 v23, v6
	v_mov_b32_e32 v24, v6
	v_mov_b32_e32 v25, v6
	v_mov_b32_e32 v26, v6
	v_mov_b32_e32 v27, v6
	v_add_co_u32_e32 v28, vcc, s28, v2
	s_nop 0
	v_addc_co_u32_e32 v29, vcc, -1, v3, vcc
	global_load_dwordx2 v[52:53], v[28:29], off nt
	v_add_co_u32_e32 v28, vcc, s29, v2
	s_nop 0
	v_addc_co_u32_e32 v29, vcc, -1, v3, vcc
	global_load_dwordx2 v[54:55], v[28:29], off nt
	v_add_co_u32_e32 v28, vcc, s22, v2
	s_nop 0
	v_addc_co_u32_e32 v29, vcc, -1, v3, vcc
	global_load_dwordx2 v[56:57], v[28:29], off nt
	v_add_co_u32_e32 v28, vcc, s23, v2
	s_nop 0
	v_addc_co_u32_e32 v29, vcc, -1, v3, vcc
	global_load_dwordx2 v[58:59], v[28:29], off nt
	v_add_co_u32_e32 v28, vcc, s26, v2
	s_nop 1
	v_addc_co_u32_e32 v29, vcc, -1, v3, vcc
	global_load_dwordx2 v[60:61], v[28:29], off nt
	v_add_co_u32_e32 v28, vcc, s27, v2
	s_nop 1
	v_addc_co_u32_e32 v29, vcc, -1, v3, vcc
	global_load_dwordx2 v[62:63], v[28:29], off nt
	v_add_co_u32_e32 v28, vcc, s95, v2
	s_nop 1
	v_addc_co_u32_e32 v29, vcc, -1, v3, vcc
	global_load_dwordx2 v[64:65], v[28:29], off nt
	global_load_dwordx2 v[66:67], v[2:3], off nt
	v_lshl_add_u64 v[2:3], v[2:3], 0, s[54:55]
	v_add_co_u32_e32 v28, vcc, s28, v2
	s_nop 0
	v_addc_co_u32_e32 v29, vcc, -1, v3, vcc
	global_load_dwordx2 v[84:85], v[28:29], off nt
	v_add_co_u32_e32 v28, vcc, s29, v2
	s_nop 0
	v_addc_co_u32_e32 v29, vcc, -1, v3, vcc
	global_load_dwordx2 v[86:87], v[28:29], off nt
	v_add_co_u32_e32 v28, vcc, s22, v2
	s_nop 0
	v_addc_co_u32_e32 v29, vcc, -1, v3, vcc
	global_load_dwordx2 v[88:89], v[28:29], off nt
	v_add_co_u32_e32 v28, vcc, s23, v2
	s_nop 0
	v_addc_co_u32_e32 v29, vcc, -1, v3, vcc
	global_load_dwordx2 v[90:91], v[28:29], off nt
	v_add_co_u32_e32 v28, vcc, s26, v2
	s_nop 1
	v_addc_co_u32_e32 v29, vcc, -1, v3, vcc
	global_load_dwordx2 v[92:93], v[28:29], off nt
	v_add_co_u32_e32 v28, vcc, s27, v2
	s_nop 1
	v_addc_co_u32_e32 v29, vcc, -1, v3, vcc
	global_load_dwordx2 v[94:95], v[28:29], off nt
	v_add_co_u32_e32 v28, vcc, s95, v2
	s_nop 1
	v_addc_co_u32_e32 v29, vcc, -1, v3, vcc
	global_load_dwordx2 v[96:97], v[28:29], off nt
	global_load_dwordx2 v[98:99], v[2:3], off nt
.LBB0_475:
	v_lshl_add_u64 v[2:3], v[2:3], 0, s[54:55]
	v_add_co_u32_e32 v28, vcc, s28, v2
	s_nop 0
	v_addc_co_u32_e32 v29, vcc, -1, v3, vcc
	global_load_dwordx2 v[116:117], v[28:29], off nt
	v_add_co_u32_e32 v28, vcc, s29, v2
	s_nop 0
	v_addc_co_u32_e32 v29, vcc, -1, v3, vcc
	global_load_dwordx2 v[118:119], v[28:29], off nt
	v_add_co_u32_e32 v28, vcc, s22, v2
	s_nop 0
	v_addc_co_u32_e32 v29, vcc, -1, v3, vcc
	global_load_dwordx2 v[120:121], v[28:29], off nt
	v_add_co_u32_e32 v28, vcc, s23, v2
	s_nop 0
	v_addc_co_u32_e32 v29, vcc, -1, v3, vcc
	global_load_dwordx2 v[122:123], v[28:29], off nt
	v_add_co_u32_e32 v28, vcc, s26, v2
	s_nop 1
	v_addc_co_u32_e32 v29, vcc, -1, v3, vcc
	global_load_dwordx2 v[124:125], v[28:29], off nt
	v_add_co_u32_e32 v28, vcc, s27, v2
	s_nop 1
	v_addc_co_u32_e32 v29, vcc, -1, v3, vcc
	global_load_dwordx2 v[126:127], v[28:29], off nt
	v_add_co_u32_e32 v28, vcc, s95, v2
	s_nop 1
	v_addc_co_u32_e32 v29, vcc, -1, v3, vcc
	global_load_dwordx2 v[128:129], v[28:29], off nt
	global_load_dwordx2 v[130:131], v[2:3], off nt
	v_mov_b32_e32 v5, s6
	s_add_i32 s6, s6, 32
	ds_read_b128 v[28:31], v5
	ds_read_b128 v[32:35], v5 offset:16
	ds_read_b128 v[36:39], v5 offset:1024
	ds_read_b128 v[40:43], v5 offset:3072
	ds_read_b128 v[44:47], v5 offset:5120
	ds_read_b128 v[48:51], v5 offset:7168
	s_waitcnt vmcnt(23) lgkmcnt(5)
	v_pk_fma_f32 v[68:69], v[52:53], v[28:29], v[6:7] op_sel_hi:[1,0,1]
	s_waitcnt lgkmcnt(3)
	v_pk_fma_f32 v[70:71], v[52:53], v[36:37], v[8:9] op_sel_hi:[1,0,1]
	ds_read_b128 v[6:9], v5 offset:2048
	s_waitcnt lgkmcnt(3)
	v_pk_fma_f32 v[74:75], v[52:53], v[40:41], v[12:13] op_sel_hi:[1,0,1]
	s_waitcnt lgkmcnt(2)
	v_pk_fma_f32 v[78:79], v[52:53], v[44:45], v[20:21] op_sel_hi:[1,0,1]
	s_waitcnt lgkmcnt(1)
	v_pk_fma_f32 v[82:83], v[52:53], v[48:49], v[24:25] op_sel_hi:[1,0,1]
	s_waitcnt vmcnt(22)
	v_pk_fma_f32 v[28:29], v[54:55], v[28:29], v[68:69] op_sel:[0,1,0]
	s_waitcnt lgkmcnt(0)
	v_pk_fma_f32 v[72:73], v[52:53], v[6:7], v[10:11] op_sel_hi:[1,0,1]
	ds_read_b128 v[10:13], v5 offset:4096
	v_pk_fma_f32 v[6:7], v[54:55], v[6:7], v[72:73] op_sel:[0,1,0]
	v_pk_fma_f32 v[36:37], v[54:55], v[36:37], v[70:71] op_sel:[0,1,0]
	v_pk_fma_f32 v[40:41], v[54:55], v[40:41], v[74:75] op_sel:[0,1,0]
	s_waitcnt vmcnt(21)
	v_pk_fma_f32 v[6:7], v[56:57], v[8:9], v[6:7] op_sel_hi:[1,0,1]
	s_waitcnt lgkmcnt(0)
	v_pk_fma_f32 v[76:77], v[52:53], v[10:11], v[18:19] op_sel_hi:[1,0,1]
	ds_read_b128 v[18:21], v5 offset:6144
	v_mov_b32_e32 v8, v31
	v_pk_fma_f32 v[10:11], v[54:55], v[10:11], v[76:77] op_sel:[0,1,0]
	v_pk_fma_f32 v[44:45], v[54:55], v[44:45], v[78:79] op_sel:[0,1,0]
	v_pk_fma_f32 v[10:11], v[56:57], v[12:13], v[10:11] op_sel_hi:[1,0,1]
	s_waitcnt lgkmcnt(0)
	v_pk_fma_f32 v[80:81], v[52:53], v[18:19], v[22:23] op_sel_hi:[1,0,1]
	ds_read_b128 v[22:25], v5 offset:8192
	v_pk_fma_f32 v[18:19], v[54:55], v[18:19], v[80:81] op_sel:[0,1,0]
	v_pk_fma_f32 v[48:49], v[54:55], v[48:49], v[82:83] op_sel:[0,1,0]
	v_pk_fma_f32 v[18:19], v[56:57], v[20:21], v[18:19] op_sel_hi:[1,0,1]
	s_waitcnt lgkmcnt(0)
	v_pk_fma_f32 v[26:27], v[52:53], v[22:23], v[26:27] op_sel_hi:[1,0,1]
	s_nop 0
	v_pk_fma_f32 v[22:23], v[54:55], v[22:23], v[26:27] op_sel:[0,1,0]
	v_pk_fma_f32 v[26:27], v[56:57], v[30:31], v[28:29] op_sel_hi:[1,0,1]
	v_pk_fma_f32 v[28:29], v[56:57], v[38:39], v[36:37] op_sel_hi:[1,0,1]
	s_waitcnt vmcnt(20)
	v_pk_fma_f32 v[26:27], v[58:59], v[8:9], v[26:27] op_sel_hi:[1,0,1]
	v_mov_b32_e32 v8, v39
	v_pk_fma_f32 v[28:29], v[58:59], v[8:9], v[28:29] op_sel_hi:[1,0,1]
	v_mov_b32_e32 v8, v9
	v_pk_fma_f32 v[36:37], v[56:57], v[42:43], v[40:41] op_sel_hi:[1,0,1]
	v_pk_fma_f32 v[30:31], v[58:59], v[8:9], v[6:7] op_sel_hi:[1,0,1]
	v_mov_b32_e32 v6, v43
	v_pk_fma_f32 v[36:37], v[58:59], v[6:7], v[36:37] op_sel_hi:[1,0,1]
	v_mov_b32_e32 v6, v13
	v_pk_fma_f32 v[40:41], v[56:57], v[46:47], v[44:45] op_sel_hi:[1,0,1]
	v_pk_fma_f32 v[38:39], v[58:59], v[6:7], v[10:11] op_sel_hi:[1,0,1]
	v_mov_b32_e32 v6, v47
	v_pk_fma_f32 v[40:41], v[58:59], v[6:7], v[40:41] op_sel_hi:[1,0,1]
	v_mov_b32_e32 v6, v21
	v_pk_fma_f32 v[44:45], v[56:57], v[50:51], v[48:49] op_sel_hi:[1,0,1]
	v_pk_fma_f32 v[42:43], v[58:59], v[6:7], v[18:19] op_sel_hi:[1,0,1]
	v_mov_b32_e32 v6, v51
	v_pk_fma_f32 v[22:23], v[56:57], v[24:25], v[22:23] op_sel_hi:[1,0,1]
	v_pk_fma_f32 v[44:45], v[58:59], v[6:7], v[44:45] op_sel_hi:[1,0,1]
	v_mov_b32_e32 v6, v25
	v_pk_fma_f32 v[48:49], v[58:59], v[6:7], v[22:23] op_sel_hi:[1,0,1]
	ds_read_b128 v[6:9], v5 offset:1040
	ds_read_b128 v[10:13], v5 offset:2064
	ds_read_b128 v[18:21], v5 offset:3088
	ds_read_b128 v[22:25], v5 offset:4112
	s_waitcnt vmcnt(19)
	v_pk_fma_f32 v[50:51], v[60:61], v[32:33], v[26:27] op_sel_hi:[1,0,1]
	s_waitcnt lgkmcnt(3)
	v_pk_fma_f32 v[52:53], v[60:61], v[6:7], v[28:29] op_sel_hi:[1,0,1]
	ds_read_b128 v[26:29], v5 offset:5136
	s_waitcnt lgkmcnt(2)
	v_pk_fma_f32 v[54:55], v[60:61], v[18:19], v[36:37] op_sel_hi:[1,0,1]
	s_waitcnt lgkmcnt(1)
	v_pk_fma_f32 v[56:57], v[60:61], v[22:23], v[38:39] op_sel_hi:[1,0,1]
	ds_read_b128 v[36:39], v5 offset:6160
	v_pk_fma_f32 v[30:31], v[60:61], v[10:11], v[30:31] op_sel_hi:[1,0,1]
	s_waitcnt lgkmcnt(1)
	v_pk_fma_f32 v[58:59], v[60:61], v[26:27], v[40:41] op_sel_hi:[1,0,1]
	s_waitcnt vmcnt(18)
	v_pk_fma_f32 v[10:11], v[62:63], v[10:11], v[30:31] op_sel:[0,1,0]
	v_pk_fma_f32 v[18:19], v[62:63], v[18:19], v[54:55] op_sel:[0,1,0]
	s_waitcnt lgkmcnt(0)
	v_pk_fma_f32 v[68:69], v[60:61], v[36:37], v[42:43] op_sel_hi:[1,0,1]
	ds_read_b128 v[40:43], v5 offset:7184
	s_waitcnt vmcnt(17)
	v_pk_fma_f32 v[10:11], v[64:65], v[12:13], v[10:11] op_sel_hi:[1,0,1]
	v_mov_b32_e32 v12, v13
	v_pk_fma_f32 v[22:23], v[62:63], v[22:23], v[56:57] op_sel:[0,1,0]
	v_pk_fma_f32 v[26:27], v[62:63], v[26:27], v[58:59] op_sel:[0,1,0]
	s_waitcnt lgkmcnt(0)
	v_pk_fma_f32 v[70:71], v[60:61], v[40:41], v[44:45] op_sel_hi:[1,0,1]
	ds_read_b128 v[44:47], v5 offset:8208
	v_pk_fma_f32 v[18:19], v[64:65], v[20:21], v[18:19] op_sel_hi:[1,0,1]
	s_waitcnt vmcnt(16)
	v_pk_fma_f32 v[10:11], v[66:67], v[12:13], v[10:11] op_sel_hi:[1,0,1]
	v_mov_b32_e32 v12, v21
	v_pk_fma_f32 v[32:33], v[62:63], v[32:33], v[50:51] op_sel:[0,1,0]
	s_waitcnt lgkmcnt(0)
	v_pk_fma_f32 v[48:49], v[60:61], v[44:45], v[48:49] op_sel_hi:[1,0,1]
	v_pk_fma_f32 v[6:7], v[62:63], v[6:7], v[52:53] op_sel:[0,1,0]
	v_pk_fma_f32 v[30:31], v[62:63], v[36:37], v[68:69] op_sel:[0,1,0]
	v_pk_fma_f32 v[36:37], v[62:63], v[40:41], v[70:71] op_sel:[0,1,0]
	v_pk_fma_f32 v[40:41], v[62:63], v[44:45], v[48:49] op_sel:[0,1,0]
	v_pk_fma_f32 v[22:23], v[64:65], v[24:25], v[22:23] op_sel_hi:[1,0,1]
	v_pk_fma_f32 v[26:27], v[64:65], v[28:29], v[26:27] op_sel_hi:[1,0,1]
	v_pk_fma_f32 v[12:13], v[66:67], v[12:13], v[18:19] op_sel_hi:[1,0,1]
	v_mov_b32_e32 v18, v25
	v_mov_b32_e32 v20, v29
	v_pk_fma_f32 v[32:33], v[64:65], v[34:35], v[32:33] op_sel_hi:[1,0,1]
	v_pk_fma_f32 v[44:45], v[64:65], v[8:9], v[6:7] op_sel_hi:[1,0,1]
	v_pk_fma_f32 v[30:31], v[64:65], v[38:39], v[30:31] op_sel_hi:[1,0,1]
	v_pk_fma_f32 v[36:37], v[64:65], v[42:43], v[36:37] op_sel_hi:[1,0,1]
	v_pk_fma_f32 v[40:41], v[64:65], v[46:47], v[40:41] op_sel_hi:[1,0,1]
	v_mov_b32_e32 v6, v35
	v_mov_b32_e32 v8, v9
	v_pk_fma_f32 v[18:19], v[66:67], v[18:19], v[22:23] op_sel_hi:[1,0,1]
	v_pk_fma_f32 v[20:21], v[66:67], v[20:21], v[26:27] op_sel_hi:[1,0,1]
	v_mov_b32_e32 v22, v39
	v_mov_b32_e32 v24, v43
	v_mov_b32_e32 v26, v47
	v_pk_fma_f32 v[6:7], v[66:67], v[6:7], v[32:33] op_sel_hi:[1,0,1]
	v_pk_fma_f32 v[8:9], v[66:67], v[8:9], v[44:45] op_sel_hi:[1,0,1]
	v_pk_fma_f32 v[22:23], v[66:67], v[22:23], v[30:31] op_sel_hi:[1,0,1]
	v_pk_fma_f32 v[24:25], v[66:67], v[24:25], v[36:37] op_sel_hi:[1,0,1]
	v_pk_fma_f32 v[26:27], v[66:67], v[26:27], v[40:41] op_sel_hi:[1,0,1]
	v_lshl_add_u64 v[2:3], v[2:3], 0, s[54:55]
	v_add_co_u32_e32 v28, vcc, s28, v2
	s_nop 0
	v_addc_co_u32_e32 v29, vcc, -1, v3, vcc
	global_load_dwordx2 v[52:53], v[28:29], off nt
	v_add_co_u32_e32 v28, vcc, s29, v2
	s_nop 0
	v_addc_co_u32_e32 v29, vcc, -1, v3, vcc
	global_load_dwordx2 v[54:55], v[28:29], off nt
	v_add_co_u32_e32 v28, vcc, s22, v2
	s_nop 0
	v_addc_co_u32_e32 v29, vcc, -1, v3, vcc
	global_load_dwordx2 v[56:57], v[28:29], off nt
	v_add_co_u32_e32 v28, vcc, s23, v2
	s_nop 0
	v_addc_co_u32_e32 v29, vcc, -1, v3, vcc
	global_load_dwordx2 v[58:59], v[28:29], off nt
	v_add_co_u32_e32 v28, vcc, s26, v2
	s_nop 1
	v_addc_co_u32_e32 v29, vcc, -1, v3, vcc
	global_load_dwordx2 v[60:61], v[28:29], off nt
	v_add_co_u32_e32 v28, vcc, s27, v2
	s_nop 1
	v_addc_co_u32_e32 v29, vcc, -1, v3, vcc
	global_load_dwordx2 v[62:63], v[28:29], off nt
	v_add_co_u32_e32 v28, vcc, s95, v2
	s_nop 1
	v_addc_co_u32_e32 v29, vcc, -1, v3, vcc
	global_load_dwordx2 v[64:65], v[28:29], off nt
	global_load_dwordx2 v[66:67], v[2:3], off nt
	v_mov_b32_e32 v5, s6
	s_add_i32 s6, s6, 32
	ds_read_b128 v[28:31], v5
	ds_read_b128 v[32:35], v5 offset:16
	ds_read_b128 v[36:39], v5 offset:1024
	ds_read_b128 v[40:43], v5 offset:3072
	ds_read_b128 v[44:47], v5 offset:5120
	ds_read_b128 v[48:51], v5 offset:7168
	s_waitcnt vmcnt(23) lgkmcnt(5)
	v_pk_fma_f32 v[68:69], v[84:85], v[28:29], v[6:7] op_sel_hi:[1,0,1]
	s_waitcnt lgkmcnt(3)
	v_pk_fma_f32 v[70:71], v[84:85], v[36:37], v[8:9] op_sel_hi:[1,0,1]
	ds_read_b128 v[6:9], v5 offset:2048
	s_waitcnt lgkmcnt(3)
	v_pk_fma_f32 v[74:75], v[84:85], v[40:41], v[12:13] op_sel_hi:[1,0,1]
	s_waitcnt lgkmcnt(2)
	v_pk_fma_f32 v[78:79], v[84:85], v[44:45], v[20:21] op_sel_hi:[1,0,1]
	s_waitcnt lgkmcnt(1)
	v_pk_fma_f32 v[82:83], v[84:85], v[48:49], v[24:25] op_sel_hi:[1,0,1]
	s_waitcnt vmcnt(22)
	v_pk_fma_f32 v[28:29], v[86:87], v[28:29], v[68:69] op_sel:[0,1,0]
	s_waitcnt lgkmcnt(0)
	v_pk_fma_f32 v[72:73], v[84:85], v[6:7], v[10:11] op_sel_hi:[1,0,1]
	ds_read_b128 v[10:13], v5 offset:4096
	v_pk_fma_f32 v[6:7], v[86:87], v[6:7], v[72:73] op_sel:[0,1,0]
	v_pk_fma_f32 v[36:37], v[86:87], v[36:37], v[70:71] op_sel:[0,1,0]
	v_pk_fma_f32 v[40:41], v[86:87], v[40:41], v[74:75] op_sel:[0,1,0]
	s_waitcnt vmcnt(21)
	v_pk_fma_f32 v[6:7], v[88:89], v[8:9], v[6:7] op_sel_hi:[1,0,1]
	s_waitcnt lgkmcnt(0)
	v_pk_fma_f32 v[76:77], v[84:85], v[10:11], v[18:19] op_sel_hi:[1,0,1]
	ds_read_b128 v[18:21], v5 offset:6144
	v_mov_b32_e32 v8, v31
	v_pk_fma_f32 v[10:11], v[86:87], v[10:11], v[76:77] op_sel:[0,1,0]
	v_pk_fma_f32 v[44:45], v[86:87], v[44:45], v[78:79] op_sel:[0,1,0]
	v_pk_fma_f32 v[10:11], v[88:89], v[12:13], v[10:11] op_sel_hi:[1,0,1]
	s_waitcnt lgkmcnt(0)
	v_pk_fma_f32 v[80:81], v[84:85], v[18:19], v[22:23] op_sel_hi:[1,0,1]
	ds_read_b128 v[22:25], v5 offset:8192
	v_pk_fma_f32 v[18:19], v[86:87], v[18:19], v[80:81] op_sel:[0,1,0]
	v_pk_fma_f32 v[48:49], v[86:87], v[48:49], v[82:83] op_sel:[0,1,0]
	v_pk_fma_f32 v[18:19], v[88:89], v[20:21], v[18:19] op_sel_hi:[1,0,1]
	s_waitcnt lgkmcnt(0)
	v_pk_fma_f32 v[26:27], v[84:85], v[22:23], v[26:27] op_sel_hi:[1,0,1]
	s_nop 0
	v_pk_fma_f32 v[22:23], v[86:87], v[22:23], v[26:27] op_sel:[0,1,0]
	v_pk_fma_f32 v[26:27], v[88:89], v[30:31], v[28:29] op_sel_hi:[1,0,1]
	v_pk_fma_f32 v[28:29], v[88:89], v[38:39], v[36:37] op_sel_hi:[1,0,1]
	s_waitcnt vmcnt(20)
	v_pk_fma_f32 v[26:27], v[90:91], v[8:9], v[26:27] op_sel_hi:[1,0,1]
	v_mov_b32_e32 v8, v39
	v_pk_fma_f32 v[28:29], v[90:91], v[8:9], v[28:29] op_sel_hi:[1,0,1]
	v_mov_b32_e32 v8, v9
	v_pk_fma_f32 v[36:37], v[88:89], v[42:43], v[40:41] op_sel_hi:[1,0,1]
	v_pk_fma_f32 v[30:31], v[90:91], v[8:9], v[6:7] op_sel_hi:[1,0,1]
	v_mov_b32_e32 v6, v43
	v_pk_fma_f32 v[36:37], v[90:91], v[6:7], v[36:37] op_sel_hi:[1,0,1]
	v_mov_b32_e32 v6, v13
	v_pk_fma_f32 v[40:41], v[88:89], v[46:47], v[44:45] op_sel_hi:[1,0,1]
	v_pk_fma_f32 v[38:39], v[90:91], v[6:7], v[10:11] op_sel_hi:[1,0,1]
	v_mov_b32_e32 v6, v47
	v_pk_fma_f32 v[40:41], v[90:91], v[6:7], v[40:41] op_sel_hi:[1,0,1]
	v_mov_b32_e32 v6, v21
	v_pk_fma_f32 v[44:45], v[88:89], v[50:51], v[48:49] op_sel_hi:[1,0,1]
	v_pk_fma_f32 v[42:43], v[90:91], v[6:7], v[18:19] op_sel_hi:[1,0,1]
	v_mov_b32_e32 v6, v51
	v_pk_fma_f32 v[22:23], v[88:89], v[24:25], v[22:23] op_sel_hi:[1,0,1]
	v_pk_fma_f32 v[44:45], v[90:91], v[6:7], v[44:45] op_sel_hi:[1,0,1]
	v_mov_b32_e32 v6, v25
	v_pk_fma_f32 v[48:49], v[90:91], v[6:7], v[22:23] op_sel_hi:[1,0,1]
	ds_read_b128 v[6:9], v5 offset:1040
	ds_read_b128 v[10:13], v5 offset:2064
	ds_read_b128 v[18:21], v5 offset:3088
	ds_read_b128 v[22:25], v5 offset:4112
	s_waitcnt vmcnt(19)
	v_pk_fma_f32 v[50:51], v[92:93], v[32:33], v[26:27] op_sel_hi:[1,0,1]
	s_waitcnt lgkmcnt(3)
	v_pk_fma_f32 v[84:85], v[92:93], v[6:7], v[28:29] op_sel_hi:[1,0,1]
	ds_read_b128 v[26:29], v5 offset:5136
	s_waitcnt lgkmcnt(2)
	v_pk_fma_f32 v[86:87], v[92:93], v[18:19], v[36:37] op_sel_hi:[1,0,1]
	s_waitcnt lgkmcnt(1)
	v_pk_fma_f32 v[88:89], v[92:93], v[22:23], v[38:39] op_sel_hi:[1,0,1]
	ds_read_b128 v[36:39], v5 offset:6160
	v_pk_fma_f32 v[30:31], v[92:93], v[10:11], v[30:31] op_sel_hi:[1,0,1]
	s_waitcnt lgkmcnt(1)
	v_pk_fma_f32 v[90:91], v[92:93], v[26:27], v[40:41] op_sel_hi:[1,0,1]
	s_waitcnt vmcnt(18)
	v_pk_fma_f32 v[10:11], v[94:95], v[10:11], v[30:31] op_sel:[0,1,0]
	v_pk_fma_f32 v[18:19], v[94:95], v[18:19], v[86:87] op_sel:[0,1,0]
	s_waitcnt lgkmcnt(0)
	v_pk_fma_f32 v[68:69], v[92:93], v[36:37], v[42:43] op_sel_hi:[1,0,1]
	ds_read_b128 v[40:43], v5 offset:7184
	s_waitcnt vmcnt(17)
	v_pk_fma_f32 v[10:11], v[96:97], v[12:13], v[10:11] op_sel_hi:[1,0,1]
	v_mov_b32_e32 v12, v13
	v_pk_fma_f32 v[22:23], v[94:95], v[22:23], v[88:89] op_sel:[0,1,0]
	v_pk_fma_f32 v[26:27], v[94:95], v[26:27], v[90:91] op_sel:[0,1,0]
	s_waitcnt lgkmcnt(0)
	v_pk_fma_f32 v[70:71], v[92:93], v[40:41], v[44:45] op_sel_hi:[1,0,1]
	ds_read_b128 v[44:47], v5 offset:8208
	v_pk_fma_f32 v[18:19], v[96:97], v[20:21], v[18:19] op_sel_hi:[1,0,1]
	s_waitcnt vmcnt(16)
	v_pk_fma_f32 v[10:11], v[98:99], v[12:13], v[10:11] op_sel_hi:[1,0,1]
	v_mov_b32_e32 v12, v21
	v_pk_fma_f32 v[32:33], v[94:95], v[32:33], v[50:51] op_sel:[0,1,0]
	s_waitcnt lgkmcnt(0)
	v_pk_fma_f32 v[48:49], v[92:93], v[44:45], v[48:49] op_sel_hi:[1,0,1]
	v_pk_fma_f32 v[6:7], v[94:95], v[6:7], v[84:85] op_sel:[0,1,0]
	v_pk_fma_f32 v[30:31], v[94:95], v[36:37], v[68:69] op_sel:[0,1,0]
	v_pk_fma_f32 v[36:37], v[94:95], v[40:41], v[70:71] op_sel:[0,1,0]
	v_pk_fma_f32 v[40:41], v[94:95], v[44:45], v[48:49] op_sel:[0,1,0]
	v_pk_fma_f32 v[22:23], v[96:97], v[24:25], v[22:23] op_sel_hi:[1,0,1]
	v_pk_fma_f32 v[26:27], v[96:97], v[28:29], v[26:27] op_sel_hi:[1,0,1]
	v_pk_fma_f32 v[12:13], v[98:99], v[12:13], v[18:19] op_sel_hi:[1,0,1]
	v_mov_b32_e32 v18, v25
	v_mov_b32_e32 v20, v29
	v_pk_fma_f32 v[32:33], v[96:97], v[34:35], v[32:33] op_sel_hi:[1,0,1]
	v_pk_fma_f32 v[44:45], v[96:97], v[8:9], v[6:7] op_sel_hi:[1,0,1]
	v_pk_fma_f32 v[30:31], v[96:97], v[38:39], v[30:31] op_sel_hi:[1,0,1]
	v_pk_fma_f32 v[36:37], v[96:97], v[42:43], v[36:37] op_sel_hi:[1,0,1]
	v_pk_fma_f32 v[40:41], v[96:97], v[46:47], v[40:41] op_sel_hi:[1,0,1]
	v_mov_b32_e32 v6, v35
	v_mov_b32_e32 v8, v9
	v_pk_fma_f32 v[18:19], v[98:99], v[18:19], v[22:23] op_sel_hi:[1,0,1]
	v_pk_fma_f32 v[20:21], v[98:99], v[20:21], v[26:27] op_sel_hi:[1,0,1]
	v_mov_b32_e32 v22, v39
	v_mov_b32_e32 v24, v43
	v_mov_b32_e32 v26, v47
	v_pk_fma_f32 v[6:7], v[98:99], v[6:7], v[32:33] op_sel_hi:[1,0,1]
	v_pk_fma_f32 v[8:9], v[98:99], v[8:9], v[44:45] op_sel_hi:[1,0,1]
	v_pk_fma_f32 v[22:23], v[98:99], v[22:23], v[30:31] op_sel_hi:[1,0,1]
	v_pk_fma_f32 v[24:25], v[98:99], v[24:25], v[36:37] op_sel_hi:[1,0,1]
	v_pk_fma_f32 v[26:27], v[98:99], v[26:27], v[40:41] op_sel_hi:[1,0,1]
	v_lshl_add_u64 v[2:3], v[2:3], 0, s[54:55]
	v_add_co_u32_e32 v28, vcc, s28, v2
	s_nop 0
	v_addc_co_u32_e32 v29, vcc, -1, v3, vcc
	global_load_dwordx2 v[84:85], v[28:29], off nt
	v_add_co_u32_e32 v28, vcc, s29, v2
	s_nop 0
	v_addc_co_u32_e32 v29, vcc, -1, v3, vcc
	global_load_dwordx2 v[86:87], v[28:29], off nt
	v_add_co_u32_e32 v28, vcc, s22, v2
	s_nop 0
	v_addc_co_u32_e32 v29, vcc, -1, v3, vcc
	global_load_dwordx2 v[88:89], v[28:29], off nt
	v_add_co_u32_e32 v28, vcc, s23, v2
	s_nop 0
	v_addc_co_u32_e32 v29, vcc, -1, v3, vcc
	global_load_dwordx2 v[90:91], v[28:29], off nt
	v_add_co_u32_e32 v28, vcc, s26, v2
	s_nop 1
	v_addc_co_u32_e32 v29, vcc, -1, v3, vcc
	global_load_dwordx2 v[92:93], v[28:29], off nt
	v_add_co_u32_e32 v28, vcc, s27, v2
	s_nop 1
	v_addc_co_u32_e32 v29, vcc, -1, v3, vcc
	global_load_dwordx2 v[94:95], v[28:29], off nt
	v_add_co_u32_e32 v28, vcc, s95, v2
	s_nop 1
	v_addc_co_u32_e32 v29, vcc, -1, v3, vcc
	global_load_dwordx2 v[96:97], v[28:29], off nt
	global_load_dwordx2 v[98:99], v[2:3], off nt
	v_mov_b32_e32 v5, s6
	s_add_i32 s6, s6, 32
	ds_read_b128 v[28:31], v5
	ds_read_b128 v[32:35], v5 offset:16
	ds_read_b128 v[36:39], v5 offset:1024
	ds_read_b128 v[40:43], v5 offset:3072
	ds_read_b128 v[44:47], v5 offset:5120
	ds_read_b128 v[48:51], v5 offset:7168
	s_waitcnt vmcnt(23) lgkmcnt(5)
	v_pk_fma_f32 v[68:69], v[116:117], v[28:29], v[6:7] op_sel_hi:[1,0,1]
	s_waitcnt lgkmcnt(3)
	v_pk_fma_f32 v[70:71], v[116:117], v[36:37], v[8:9] op_sel_hi:[1,0,1]
	ds_read_b128 v[6:9], v5 offset:2048
	s_waitcnt lgkmcnt(3)
	v_pk_fma_f32 v[74:75], v[116:117], v[40:41], v[12:13] op_sel_hi:[1,0,1]
	s_waitcnt lgkmcnt(2)
	v_pk_fma_f32 v[78:79], v[116:117], v[44:45], v[20:21] op_sel_hi:[1,0,1]
	s_waitcnt lgkmcnt(1)
	v_pk_fma_f32 v[82:83], v[116:117], v[48:49], v[24:25] op_sel_hi:[1,0,1]
	s_waitcnt vmcnt(22)
	v_pk_fma_f32 v[28:29], v[118:119], v[28:29], v[68:69] op_sel:[0,1,0]
	s_waitcnt lgkmcnt(0)
	v_pk_fma_f32 v[72:73], v[116:117], v[6:7], v[10:11] op_sel_hi:[1,0,1]
	ds_read_b128 v[10:13], v5 offset:4096
	v_pk_fma_f32 v[6:7], v[118:119], v[6:7], v[72:73] op_sel:[0,1,0]
	v_pk_fma_f32 v[36:37], v[118:119], v[36:37], v[70:71] op_sel:[0,1,0]
	v_pk_fma_f32 v[40:41], v[118:119], v[40:41], v[74:75] op_sel:[0,1,0]
	s_waitcnt vmcnt(21)
	v_pk_fma_f32 v[6:7], v[120:121], v[8:9], v[6:7] op_sel_hi:[1,0,1]
	s_waitcnt lgkmcnt(0)
	v_pk_fma_f32 v[76:77], v[116:117], v[10:11], v[18:19] op_sel_hi:[1,0,1]
	ds_read_b128 v[18:21], v5 offset:6144
	v_mov_b32_e32 v8, v31
	v_pk_fma_f32 v[10:11], v[118:119], v[10:11], v[76:77] op_sel:[0,1,0]
	v_pk_fma_f32 v[44:45], v[118:119], v[44:45], v[78:79] op_sel:[0,1,0]
	v_pk_fma_f32 v[10:11], v[120:121], v[12:13], v[10:11] op_sel_hi:[1,0,1]
	s_waitcnt lgkmcnt(0)
	v_pk_fma_f32 v[80:81], v[116:117], v[18:19], v[22:23] op_sel_hi:[1,0,1]
	ds_read_b128 v[22:25], v5 offset:8192
	v_pk_fma_f32 v[18:19], v[118:119], v[18:19], v[80:81] op_sel:[0,1,0]
	v_pk_fma_f32 v[48:49], v[118:119], v[48:49], v[82:83] op_sel:[0,1,0]
	v_pk_fma_f32 v[18:19], v[120:121], v[20:21], v[18:19] op_sel_hi:[1,0,1]
	s_waitcnt lgkmcnt(0)
	v_pk_fma_f32 v[26:27], v[116:117], v[22:23], v[26:27] op_sel_hi:[1,0,1]
	s_nop 0
	v_pk_fma_f32 v[22:23], v[118:119], v[22:23], v[26:27] op_sel:[0,1,0]
	v_pk_fma_f32 v[26:27], v[120:121], v[30:31], v[28:29] op_sel_hi:[1,0,1]
	v_pk_fma_f32 v[28:29], v[120:121], v[38:39], v[36:37] op_sel_hi:[1,0,1]
	s_waitcnt vmcnt(20)
	v_pk_fma_f32 v[26:27], v[122:123], v[8:9], v[26:27] op_sel_hi:[1,0,1]
	v_mov_b32_e32 v8, v39
	v_pk_fma_f32 v[28:29], v[122:123], v[8:9], v[28:29] op_sel_hi:[1,0,1]
	v_mov_b32_e32 v8, v9
	v_pk_fma_f32 v[36:37], v[120:121], v[42:43], v[40:41] op_sel_hi:[1,0,1]
	v_pk_fma_f32 v[30:31], v[122:123], v[8:9], v[6:7] op_sel_hi:[1,0,1]
	v_mov_b32_e32 v6, v43
	v_pk_fma_f32 v[36:37], v[122:123], v[6:7], v[36:37] op_sel_hi:[1,0,1]
	v_mov_b32_e32 v6, v13
	v_pk_fma_f32 v[40:41], v[120:121], v[46:47], v[44:45] op_sel_hi:[1,0,1]
	v_pk_fma_f32 v[38:39], v[122:123], v[6:7], v[10:11] op_sel_hi:[1,0,1]
	v_mov_b32_e32 v6, v47
	v_pk_fma_f32 v[40:41], v[122:123], v[6:7], v[40:41] op_sel_hi:[1,0,1]
	v_mov_b32_e32 v6, v21
	v_pk_fma_f32 v[44:45], v[120:121], v[50:51], v[48:49] op_sel_hi:[1,0,1]
	v_pk_fma_f32 v[42:43], v[122:123], v[6:7], v[18:19] op_sel_hi:[1,0,1]
	v_mov_b32_e32 v6, v51
	v_pk_fma_f32 v[22:23], v[120:121], v[24:25], v[22:23] op_sel_hi:[1,0,1]
	v_pk_fma_f32 v[44:45], v[122:123], v[6:7], v[44:45] op_sel_hi:[1,0,1]
	v_mov_b32_e32 v6, v25
	v_pk_fma_f32 v[48:49], v[122:123], v[6:7], v[22:23] op_sel_hi:[1,0,1]
	ds_read_b128 v[6:9], v5 offset:1040
	ds_read_b128 v[10:13], v5 offset:2064
	ds_read_b128 v[18:21], v5 offset:3088
	ds_read_b128 v[22:25], v5 offset:4112
	s_waitcnt vmcnt(19)
	v_pk_fma_f32 v[50:51], v[124:125], v[32:33], v[26:27] op_sel_hi:[1,0,1]
	s_waitcnt lgkmcnt(3)
	v_pk_fma_f32 v[116:117], v[124:125], v[6:7], v[28:29] op_sel_hi:[1,0,1]
	ds_read_b128 v[26:29], v5 offset:5136
	s_waitcnt lgkmcnt(2)
	v_pk_fma_f32 v[118:119], v[124:125], v[18:19], v[36:37] op_sel_hi:[1,0,1]
	s_waitcnt lgkmcnt(1)
	v_pk_fma_f32 v[120:121], v[124:125], v[22:23], v[38:39] op_sel_hi:[1,0,1]
	ds_read_b128 v[36:39], v5 offset:6160
	v_pk_fma_f32 v[30:31], v[124:125], v[10:11], v[30:31] op_sel_hi:[1,0,1]
	s_waitcnt lgkmcnt(1)
	v_pk_fma_f32 v[122:123], v[124:125], v[26:27], v[40:41] op_sel_hi:[1,0,1]
	s_waitcnt vmcnt(18)
	v_pk_fma_f32 v[10:11], v[126:127], v[10:11], v[30:31] op_sel:[0,1,0]
	v_pk_fma_f32 v[18:19], v[126:127], v[18:19], v[118:119] op_sel:[0,1,0]
	s_waitcnt lgkmcnt(0)
	v_pk_fma_f32 v[68:69], v[124:125], v[36:37], v[42:43] op_sel_hi:[1,0,1]
	ds_read_b128 v[40:43], v5 offset:7184
	s_waitcnt vmcnt(17)
	v_pk_fma_f32 v[10:11], v[128:129], v[12:13], v[10:11] op_sel_hi:[1,0,1]
	v_mov_b32_e32 v12, v13
	v_pk_fma_f32 v[22:23], v[126:127], v[22:23], v[120:121] op_sel:[0,1,0]
	v_pk_fma_f32 v[26:27], v[126:127], v[26:27], v[122:123] op_sel:[0,1,0]
	s_waitcnt lgkmcnt(0)
	v_pk_fma_f32 v[70:71], v[124:125], v[40:41], v[44:45] op_sel_hi:[1,0,1]
	ds_read_b128 v[44:47], v5 offset:8208
	v_pk_fma_f32 v[18:19], v[128:129], v[20:21], v[18:19] op_sel_hi:[1,0,1]
	s_waitcnt vmcnt(16)
	v_pk_fma_f32 v[10:11], v[130:131], v[12:13], v[10:11] op_sel_hi:[1,0,1]
	v_mov_b32_e32 v12, v21
	v_pk_fma_f32 v[32:33], v[126:127], v[32:33], v[50:51] op_sel:[0,1,0]
	s_waitcnt lgkmcnt(0)
	v_pk_fma_f32 v[48:49], v[124:125], v[44:45], v[48:49] op_sel_hi:[1,0,1]
	v_pk_fma_f32 v[6:7], v[126:127], v[6:7], v[116:117] op_sel:[0,1,0]
	v_pk_fma_f32 v[30:31], v[126:127], v[36:37], v[68:69] op_sel:[0,1,0]
	v_pk_fma_f32 v[36:37], v[126:127], v[40:41], v[70:71] op_sel:[0,1,0]
	v_pk_fma_f32 v[40:41], v[126:127], v[44:45], v[48:49] op_sel:[0,1,0]
	v_pk_fma_f32 v[22:23], v[128:129], v[24:25], v[22:23] op_sel_hi:[1,0,1]
	v_pk_fma_f32 v[26:27], v[128:129], v[28:29], v[26:27] op_sel_hi:[1,0,1]
	v_pk_fma_f32 v[12:13], v[130:131], v[12:13], v[18:19] op_sel_hi:[1,0,1]
	v_mov_b32_e32 v18, v25
	v_mov_b32_e32 v20, v29
	v_pk_fma_f32 v[32:33], v[128:129], v[34:35], v[32:33] op_sel_hi:[1,0,1]
	v_pk_fma_f32 v[44:45], v[128:129], v[8:9], v[6:7] op_sel_hi:[1,0,1]
	v_pk_fma_f32 v[30:31], v[128:129], v[38:39], v[30:31] op_sel_hi:[1,0,1]
	v_pk_fma_f32 v[36:37], v[128:129], v[42:43], v[36:37] op_sel_hi:[1,0,1]
	v_pk_fma_f32 v[40:41], v[128:129], v[46:47], v[40:41] op_sel_hi:[1,0,1]
	v_mov_b32_e32 v6, v35
	v_mov_b32_e32 v8, v9
	v_pk_fma_f32 v[18:19], v[130:131], v[18:19], v[22:23] op_sel_hi:[1,0,1]
	v_pk_fma_f32 v[20:21], v[130:131], v[20:21], v[26:27] op_sel_hi:[1,0,1]
	v_mov_b32_e32 v22, v39
	v_mov_b32_e32 v24, v43
	v_mov_b32_e32 v26, v47
	v_pk_fma_f32 v[6:7], v[130:131], v[6:7], v[32:33] op_sel_hi:[1,0,1]
	v_pk_fma_f32 v[8:9], v[130:131], v[8:9], v[44:45] op_sel_hi:[1,0,1]
	v_pk_fma_f32 v[22:23], v[130:131], v[22:23], v[30:31] op_sel_hi:[1,0,1]
	v_pk_fma_f32 v[24:25], v[130:131], v[24:25], v[36:37] op_sel_hi:[1,0,1]
	v_pk_fma_f32 v[26:27], v[130:131], v[26:27], v[40:41] op_sel_hi:[1,0,1]
	s_add_i32 s3, s3, 24
	s_cmpk_lt_u32 s3, 0xe8
	s_cbranch_scc1 .LBB0_475
	v_mov_b32_e32 v5, s6
	s_add_i32 s6, s6, 32
	ds_read_b128 v[28:31], v5
	ds_read_b128 v[32:35], v5 offset:16
	ds_read_b128 v[36:39], v5 offset:1024
	ds_read_b128 v[40:43], v5 offset:3072
	ds_read_b128 v[44:47], v5 offset:5120
	ds_read_b128 v[48:51], v5 offset:7168
	s_waitcnt vmcnt(15) lgkmcnt(5)
	v_pk_fma_f32 v[68:69], v[52:53], v[28:29], v[6:7] op_sel_hi:[1,0,1]
	s_waitcnt lgkmcnt(3)
	v_pk_fma_f32 v[70:71], v[52:53], v[36:37], v[8:9] op_sel_hi:[1,0,1]
	ds_read_b128 v[6:9], v5 offset:2048
	s_waitcnt lgkmcnt(3)
	v_pk_fma_f32 v[74:75], v[52:53], v[40:41], v[12:13] op_sel_hi:[1,0,1]
	s_waitcnt lgkmcnt(2)
	v_pk_fma_f32 v[78:79], v[52:53], v[44:45], v[20:21] op_sel_hi:[1,0,1]
	s_waitcnt lgkmcnt(1)
	v_pk_fma_f32 v[82:83], v[52:53], v[48:49], v[24:25] op_sel_hi:[1,0,1]
	s_waitcnt vmcnt(14)
	v_pk_fma_f32 v[28:29], v[54:55], v[28:29], v[68:69] op_sel:[0,1,0]
	s_waitcnt lgkmcnt(0)
	v_pk_fma_f32 v[72:73], v[52:53], v[6:7], v[10:11] op_sel_hi:[1,0,1]
	ds_read_b128 v[10:13], v5 offset:4096
	v_pk_fma_f32 v[6:7], v[54:55], v[6:7], v[72:73] op_sel:[0,1,0]
	v_pk_fma_f32 v[36:37], v[54:55], v[36:37], v[70:71] op_sel:[0,1,0]
	v_pk_fma_f32 v[40:41], v[54:55], v[40:41], v[74:75] op_sel:[0,1,0]
	s_waitcnt vmcnt(13)
	v_pk_fma_f32 v[6:7], v[56:57], v[8:9], v[6:7] op_sel_hi:[1,0,1]
	s_waitcnt lgkmcnt(0)
	v_pk_fma_f32 v[76:77], v[52:53], v[10:11], v[18:19] op_sel_hi:[1,0,1]
	ds_read_b128 v[18:21], v5 offset:6144
	v_mov_b32_e32 v8, v31
	v_pk_fma_f32 v[10:11], v[54:55], v[10:11], v[76:77] op_sel:[0,1,0]
	v_pk_fma_f32 v[44:45], v[54:55], v[44:45], v[78:79] op_sel:[0,1,0]
	v_pk_fma_f32 v[10:11], v[56:57], v[12:13], v[10:11] op_sel_hi:[1,0,1]
	s_waitcnt lgkmcnt(0)
	v_pk_fma_f32 v[80:81], v[52:53], v[18:19], v[22:23] op_sel_hi:[1,0,1]
	ds_read_b128 v[22:25], v5 offset:8192
	v_pk_fma_f32 v[18:19], v[54:55], v[18:19], v[80:81] op_sel:[0,1,0]
	v_pk_fma_f32 v[48:49], v[54:55], v[48:49], v[82:83] op_sel:[0,1,0]
	v_pk_fma_f32 v[18:19], v[56:57], v[20:21], v[18:19] op_sel_hi:[1,0,1]
	s_waitcnt lgkmcnt(0)
	v_pk_fma_f32 v[26:27], v[52:53], v[22:23], v[26:27] op_sel_hi:[1,0,1]
	s_nop 0
	v_pk_fma_f32 v[22:23], v[54:55], v[22:23], v[26:27] op_sel:[0,1,0]
	v_pk_fma_f32 v[26:27], v[56:57], v[30:31], v[28:29] op_sel_hi:[1,0,1]
	v_pk_fma_f32 v[28:29], v[56:57], v[38:39], v[36:37] op_sel_hi:[1,0,1]
	s_waitcnt vmcnt(12)
	v_pk_fma_f32 v[26:27], v[58:59], v[8:9], v[26:27] op_sel_hi:[1,0,1]
	v_mov_b32_e32 v8, v39
	v_pk_fma_f32 v[28:29], v[58:59], v[8:9], v[28:29] op_sel_hi:[1,0,1]
	v_mov_b32_e32 v8, v9
	v_pk_fma_f32 v[36:37], v[56:57], v[42:43], v[40:41] op_sel_hi:[1,0,1]
	v_pk_fma_f32 v[30:31], v[58:59], v[8:9], v[6:7] op_sel_hi:[1,0,1]
	v_mov_b32_e32 v6, v43
	v_pk_fma_f32 v[36:37], v[58:59], v[6:7], v[36:37] op_sel_hi:[1,0,1]
	v_mov_b32_e32 v6, v13
	v_pk_fma_f32 v[40:41], v[56:57], v[46:47], v[44:45] op_sel_hi:[1,0,1]
	v_pk_fma_f32 v[38:39], v[58:59], v[6:7], v[10:11] op_sel_hi:[1,0,1]
	v_mov_b32_e32 v6, v47
	v_pk_fma_f32 v[40:41], v[58:59], v[6:7], v[40:41] op_sel_hi:[1,0,1]
	v_mov_b32_e32 v6, v21
	v_pk_fma_f32 v[44:45], v[56:57], v[50:51], v[48:49] op_sel_hi:[1,0,1]
	v_pk_fma_f32 v[42:43], v[58:59], v[6:7], v[18:19] op_sel_hi:[1,0,1]
	v_mov_b32_e32 v6, v51
	v_pk_fma_f32 v[22:23], v[56:57], v[24:25], v[22:23] op_sel_hi:[1,0,1]
	v_pk_fma_f32 v[44:45], v[58:59], v[6:7], v[44:45] op_sel_hi:[1,0,1]
	v_mov_b32_e32 v6, v25
	v_pk_fma_f32 v[48:49], v[58:59], v[6:7], v[22:23] op_sel_hi:[1,0,1]
	ds_read_b128 v[6:9], v5 offset:1040
	ds_read_b128 v[10:13], v5 offset:2064
	ds_read_b128 v[18:21], v5 offset:3088
	ds_read_b128 v[22:25], v5 offset:4112
	s_waitcnt vmcnt(11)
	v_pk_fma_f32 v[50:51], v[60:61], v[32:33], v[26:27] op_sel_hi:[1,0,1]
	s_waitcnt lgkmcnt(3)
	v_pk_fma_f32 v[52:53], v[60:61], v[6:7], v[28:29] op_sel_hi:[1,0,1]
	ds_read_b128 v[26:29], v5 offset:5136
	s_waitcnt lgkmcnt(2)
	v_pk_fma_f32 v[54:55], v[60:61], v[18:19], v[36:37] op_sel_hi:[1,0,1]
	s_waitcnt lgkmcnt(1)
	v_pk_fma_f32 v[56:57], v[60:61], v[22:23], v[38:39] op_sel_hi:[1,0,1]
	ds_read_b128 v[36:39], v5 offset:6160
	v_pk_fma_f32 v[30:31], v[60:61], v[10:11], v[30:31] op_sel_hi:[1,0,1]
	s_waitcnt lgkmcnt(1)
	v_pk_fma_f32 v[58:59], v[60:61], v[26:27], v[40:41] op_sel_hi:[1,0,1]
	s_waitcnt vmcnt(10)
	v_pk_fma_f32 v[10:11], v[62:63], v[10:11], v[30:31] op_sel:[0,1,0]
	v_pk_fma_f32 v[18:19], v[62:63], v[18:19], v[54:55] op_sel:[0,1,0]
	s_waitcnt lgkmcnt(0)
	v_pk_fma_f32 v[68:69], v[60:61], v[36:37], v[42:43] op_sel_hi:[1,0,1]
	ds_read_b128 v[40:43], v5 offset:7184
	s_waitcnt vmcnt(9)
	v_pk_fma_f32 v[10:11], v[64:65], v[12:13], v[10:11] op_sel_hi:[1,0,1]
	v_mov_b32_e32 v12, v13
	v_pk_fma_f32 v[22:23], v[62:63], v[22:23], v[56:57] op_sel:[0,1,0]
	v_pk_fma_f32 v[26:27], v[62:63], v[26:27], v[58:59] op_sel:[0,1,0]
	s_waitcnt lgkmcnt(0)
	v_pk_fma_f32 v[70:71], v[60:61], v[40:41], v[44:45] op_sel_hi:[1,0,1]
	ds_read_b128 v[44:47], v5 offset:8208
	v_pk_fma_f32 v[18:19], v[64:65], v[20:21], v[18:19] op_sel_hi:[1,0,1]
	s_waitcnt vmcnt(8)
	v_pk_fma_f32 v[10:11], v[66:67], v[12:13], v[10:11] op_sel_hi:[1,0,1]
	v_mov_b32_e32 v12, v21
	v_pk_fma_f32 v[32:33], v[62:63], v[32:33], v[50:51] op_sel:[0,1,0]
	s_waitcnt lgkmcnt(0)
	v_pk_fma_f32 v[48:49], v[60:61], v[44:45], v[48:49] op_sel_hi:[1,0,1]
	v_pk_fma_f32 v[6:7], v[62:63], v[6:7], v[52:53] op_sel:[0,1,0]
	v_pk_fma_f32 v[30:31], v[62:63], v[36:37], v[68:69] op_sel:[0,1,0]
	v_pk_fma_f32 v[36:37], v[62:63], v[40:41], v[70:71] op_sel:[0,1,0]
	v_pk_fma_f32 v[40:41], v[62:63], v[44:45], v[48:49] op_sel:[0,1,0]
	v_pk_fma_f32 v[22:23], v[64:65], v[24:25], v[22:23] op_sel_hi:[1,0,1]
	v_pk_fma_f32 v[26:27], v[64:65], v[28:29], v[26:27] op_sel_hi:[1,0,1]
	v_pk_fma_f32 v[12:13], v[66:67], v[12:13], v[18:19] op_sel_hi:[1,0,1]
	v_mov_b32_e32 v18, v25
	v_mov_b32_e32 v20, v29
	v_pk_fma_f32 v[32:33], v[64:65], v[34:35], v[32:33] op_sel_hi:[1,0,1]
	v_pk_fma_f32 v[44:45], v[64:65], v[8:9], v[6:7] op_sel_hi:[1,0,1]
	v_pk_fma_f32 v[30:31], v[64:65], v[38:39], v[30:31] op_sel_hi:[1,0,1]
	v_pk_fma_f32 v[36:37], v[64:65], v[42:43], v[36:37] op_sel_hi:[1,0,1]
	v_pk_fma_f32 v[40:41], v[64:65], v[46:47], v[40:41] op_sel_hi:[1,0,1]
	v_mov_b32_e32 v6, v35
	v_mov_b32_e32 v8, v9
	v_pk_fma_f32 v[18:19], v[66:67], v[18:19], v[22:23] op_sel_hi:[1,0,1]
	v_pk_fma_f32 v[20:21], v[66:67], v[20:21], v[26:27] op_sel_hi:[1,0,1]
	v_mov_b32_e32 v22, v39
	v_mov_b32_e32 v24, v43
	v_mov_b32_e32 v26, v47
	v_pk_fma_f32 v[6:7], v[66:67], v[6:7], v[32:33] op_sel_hi:[1,0,1]
	v_pk_fma_f32 v[8:9], v[66:67], v[8:9], v[44:45] op_sel_hi:[1,0,1]
	v_pk_fma_f32 v[22:23], v[66:67], v[22:23], v[30:31] op_sel_hi:[1,0,1]
	v_pk_fma_f32 v[24:25], v[66:67], v[24:25], v[36:37] op_sel_hi:[1,0,1]
	v_pk_fma_f32 v[26:27], v[66:67], v[26:27], v[40:41] op_sel_hi:[1,0,1]
	v_mov_b32_e32 v5, s6
	s_add_i32 s6, s6, 32
	ds_read_b128 v[28:31], v5
	ds_read_b128 v[32:35], v5 offset:16
	ds_read_b128 v[36:39], v5 offset:1024
	ds_read_b128 v[40:43], v5 offset:3072
	ds_read_b128 v[44:47], v5 offset:5120
	ds_read_b128 v[48:51], v5 offset:7168
	s_waitcnt vmcnt(7) lgkmcnt(5)
	v_pk_fma_f32 v[68:69], v[84:85], v[28:29], v[6:7] op_sel_hi:[1,0,1]
	s_waitcnt lgkmcnt(3)
	v_pk_fma_f32 v[70:71], v[84:85], v[36:37], v[8:9] op_sel_hi:[1,0,1]
	ds_read_b128 v[6:9], v5 offset:2048
	s_waitcnt lgkmcnt(3)
	v_pk_fma_f32 v[74:75], v[84:85], v[40:41], v[12:13] op_sel_hi:[1,0,1]
	s_waitcnt lgkmcnt(2)
	v_pk_fma_f32 v[78:79], v[84:85], v[44:45], v[20:21] op_sel_hi:[1,0,1]
	s_waitcnt lgkmcnt(1)
	v_pk_fma_f32 v[82:83], v[84:85], v[48:49], v[24:25] op_sel_hi:[1,0,1]
	s_waitcnt vmcnt(6)
	v_pk_fma_f32 v[28:29], v[86:87], v[28:29], v[68:69] op_sel:[0,1,0]
	s_waitcnt lgkmcnt(0)
	v_pk_fma_f32 v[72:73], v[84:85], v[6:7], v[10:11] op_sel_hi:[1,0,1]
	ds_read_b128 v[10:13], v5 offset:4096
	v_pk_fma_f32 v[6:7], v[86:87], v[6:7], v[72:73] op_sel:[0,1,0]
	v_pk_fma_f32 v[36:37], v[86:87], v[36:37], v[70:71] op_sel:[0,1,0]
	v_pk_fma_f32 v[40:41], v[86:87], v[40:41], v[74:75] op_sel:[0,1,0]
	s_waitcnt vmcnt(5)
	v_pk_fma_f32 v[6:7], v[88:89], v[8:9], v[6:7] op_sel_hi:[1,0,1]
	s_waitcnt lgkmcnt(0)
	v_pk_fma_f32 v[76:77], v[84:85], v[10:11], v[18:19] op_sel_hi:[1,0,1]
	ds_read_b128 v[18:21], v5 offset:6144
	v_mov_b32_e32 v8, v31
	v_pk_fma_f32 v[10:11], v[86:87], v[10:11], v[76:77] op_sel:[0,1,0]
	v_pk_fma_f32 v[44:45], v[86:87], v[44:45], v[78:79] op_sel:[0,1,0]
	v_pk_fma_f32 v[10:11], v[88:89], v[12:13], v[10:11] op_sel_hi:[1,0,1]
	s_waitcnt lgkmcnt(0)
	v_pk_fma_f32 v[80:81], v[84:85], v[18:19], v[22:23] op_sel_hi:[1,0,1]
	ds_read_b128 v[22:25], v5 offset:8192
	v_pk_fma_f32 v[18:19], v[86:87], v[18:19], v[80:81] op_sel:[0,1,0]
	v_pk_fma_f32 v[48:49], v[86:87], v[48:49], v[82:83] op_sel:[0,1,0]
	v_pk_fma_f32 v[18:19], v[88:89], v[20:21], v[18:19] op_sel_hi:[1,0,1]
	s_waitcnt lgkmcnt(0)
	v_pk_fma_f32 v[26:27], v[84:85], v[22:23], v[26:27] op_sel_hi:[1,0,1]
	s_nop 0
	v_pk_fma_f32 v[22:23], v[86:87], v[22:23], v[26:27] op_sel:[0,1,0]
	v_pk_fma_f32 v[26:27], v[88:89], v[30:31], v[28:29] op_sel_hi:[1,0,1]
	v_pk_fma_f32 v[28:29], v[88:89], v[38:39], v[36:37] op_sel_hi:[1,0,1]
	s_waitcnt vmcnt(4)
	v_pk_fma_f32 v[26:27], v[90:91], v[8:9], v[26:27] op_sel_hi:[1,0,1]
	v_mov_b32_e32 v8, v39
	v_pk_fma_f32 v[28:29], v[90:91], v[8:9], v[28:29] op_sel_hi:[1,0,1]
	v_mov_b32_e32 v8, v9
	v_pk_fma_f32 v[36:37], v[88:89], v[42:43], v[40:41] op_sel_hi:[1,0,1]
	v_pk_fma_f32 v[30:31], v[90:91], v[8:9], v[6:7] op_sel_hi:[1,0,1]
	v_mov_b32_e32 v6, v43
	v_pk_fma_f32 v[36:37], v[90:91], v[6:7], v[36:37] op_sel_hi:[1,0,1]
	v_mov_b32_e32 v6, v13
	v_pk_fma_f32 v[40:41], v[88:89], v[46:47], v[44:45] op_sel_hi:[1,0,1]
	v_pk_fma_f32 v[38:39], v[90:91], v[6:7], v[10:11] op_sel_hi:[1,0,1]
	v_mov_b32_e32 v6, v47
	v_pk_fma_f32 v[40:41], v[90:91], v[6:7], v[40:41] op_sel_hi:[1,0,1]
	v_mov_b32_e32 v6, v21
	v_pk_fma_f32 v[44:45], v[88:89], v[50:51], v[48:49] op_sel_hi:[1,0,1]
	v_pk_fma_f32 v[42:43], v[90:91], v[6:7], v[18:19] op_sel_hi:[1,0,1]
	v_mov_b32_e32 v6, v51
	v_pk_fma_f32 v[22:23], v[88:89], v[24:25], v[22:23] op_sel_hi:[1,0,1]
	v_pk_fma_f32 v[44:45], v[90:91], v[6:7], v[44:45] op_sel_hi:[1,0,1]
	v_mov_b32_e32 v6, v25
	v_pk_fma_f32 v[48:49], v[90:91], v[6:7], v[22:23] op_sel_hi:[1,0,1]
	ds_read_b128 v[6:9], v5 offset:1040
	ds_read_b128 v[10:13], v5 offset:2064
	ds_read_b128 v[18:21], v5 offset:3088
	ds_read_b128 v[22:25], v5 offset:4112
	s_waitcnt vmcnt(3)
	v_pk_fma_f32 v[50:51], v[92:93], v[32:33], v[26:27] op_sel_hi:[1,0,1]
	s_waitcnt lgkmcnt(3)
	v_pk_fma_f32 v[84:85], v[92:93], v[6:7], v[28:29] op_sel_hi:[1,0,1]
	ds_read_b128 v[26:29], v5 offset:5136
	s_waitcnt lgkmcnt(2)
	v_pk_fma_f32 v[86:87], v[92:93], v[18:19], v[36:37] op_sel_hi:[1,0,1]
	s_waitcnt lgkmcnt(1)
	v_pk_fma_f32 v[88:89], v[92:93], v[22:23], v[38:39] op_sel_hi:[1,0,1]
	ds_read_b128 v[36:39], v5 offset:6160
	v_pk_fma_f32 v[30:31], v[92:93], v[10:11], v[30:31] op_sel_hi:[1,0,1]
	s_waitcnt lgkmcnt(1)
	v_pk_fma_f32 v[90:91], v[92:93], v[26:27], v[40:41] op_sel_hi:[1,0,1]
	s_waitcnt vmcnt(2)
	v_pk_fma_f32 v[10:11], v[94:95], v[10:11], v[30:31] op_sel:[0,1,0]
	v_pk_fma_f32 v[18:19], v[94:95], v[18:19], v[86:87] op_sel:[0,1,0]
	s_waitcnt lgkmcnt(0)
	v_pk_fma_f32 v[68:69], v[92:93], v[36:37], v[42:43] op_sel_hi:[1,0,1]
	ds_read_b128 v[40:43], v5 offset:7184
	s_waitcnt vmcnt(1)
	v_pk_fma_f32 v[10:11], v[96:97], v[12:13], v[10:11] op_sel_hi:[1,0,1]
	v_mov_b32_e32 v12, v13
	v_pk_fma_f32 v[22:23], v[94:95], v[22:23], v[88:89] op_sel:[0,1,0]
	v_pk_fma_f32 v[26:27], v[94:95], v[26:27], v[90:91] op_sel:[0,1,0]
	s_waitcnt lgkmcnt(0)
	v_pk_fma_f32 v[70:71], v[92:93], v[40:41], v[44:45] op_sel_hi:[1,0,1]
	ds_read_b128 v[44:47], v5 offset:8208
	v_pk_fma_f32 v[18:19], v[96:97], v[20:21], v[18:19] op_sel_hi:[1,0,1]
	s_waitcnt vmcnt(0)
	v_pk_fma_f32 v[10:11], v[98:99], v[12:13], v[10:11] op_sel_hi:[1,0,1]
	v_mov_b32_e32 v12, v21
	v_pk_fma_f32 v[32:33], v[94:95], v[32:33], v[50:51] op_sel:[0,1,0]
	s_waitcnt lgkmcnt(0)
	v_pk_fma_f32 v[48:49], v[92:93], v[44:45], v[48:49] op_sel_hi:[1,0,1]
	v_pk_fma_f32 v[6:7], v[94:95], v[6:7], v[84:85] op_sel:[0,1,0]
	v_pk_fma_f32 v[30:31], v[94:95], v[36:37], v[68:69] op_sel:[0,1,0]
	v_pk_fma_f32 v[36:37], v[94:95], v[40:41], v[70:71] op_sel:[0,1,0]
	v_pk_fma_f32 v[40:41], v[94:95], v[44:45], v[48:49] op_sel:[0,1,0]
	v_pk_fma_f32 v[22:23], v[96:97], v[24:25], v[22:23] op_sel_hi:[1,0,1]
	v_pk_fma_f32 v[26:27], v[96:97], v[28:29], v[26:27] op_sel_hi:[1,0,1]
	v_pk_fma_f32 v[12:13], v[98:99], v[12:13], v[18:19] op_sel_hi:[1,0,1]
	v_mov_b32_e32 v18, v25
	v_mov_b32_e32 v20, v29
	v_pk_fma_f32 v[32:33], v[96:97], v[34:35], v[32:33] op_sel_hi:[1,0,1]
	v_pk_fma_f32 v[44:45], v[96:97], v[8:9], v[6:7] op_sel_hi:[1,0,1]
	v_pk_fma_f32 v[30:31], v[96:97], v[38:39], v[30:31] op_sel_hi:[1,0,1]
	v_pk_fma_f32 v[36:37], v[96:97], v[42:43], v[36:37] op_sel_hi:[1,0,1]
	v_pk_fma_f32 v[40:41], v[96:97], v[46:47], v[40:41] op_sel_hi:[1,0,1]
	v_mov_b32_e32 v6, v35
	v_mov_b32_e32 v8, v9
	v_pk_fma_f32 v[18:19], v[98:99], v[18:19], v[22:23] op_sel_hi:[1,0,1]
	v_pk_fma_f32 v[20:21], v[98:99], v[20:21], v[26:27] op_sel_hi:[1,0,1]
	v_mov_b32_e32 v22, v39
	v_mov_b32_e32 v24, v43
	v_mov_b32_e32 v26, v47
	v_pk_fma_f32 v[6:7], v[98:99], v[6:7], v[32:33] op_sel_hi:[1,0,1]
	v_pk_fma_f32 v[8:9], v[98:99], v[8:9], v[44:45] op_sel_hi:[1,0,1]
	v_pk_fma_f32 v[22:23], v[98:99], v[22:23], v[30:31] op_sel_hi:[1,0,1]
	v_pk_fma_f32 v[24:25], v[98:99], v[24:25], v[36:37] op_sel_hi:[1,0,1]
	v_pk_fma_f32 v[26:27], v[98:99], v[26:27], v[40:41] op_sel_hi:[1,0,1]
	s_waitcnt lgkmcnt(0)
	v_add_u32_e32 v2, s34, v0
	ds_write2st64_b64 v2, v[6:7], v[8:9] offset1:1
	ds_write2st64_b64 v2, v[10:11], v[12:13] offset0:2 offset1:3
	ds_write2st64_b64 v2, v[18:19], v[20:21] offset0:4 offset1:5
	ds_write2st64_b64 v2, v[22:23], v[24:25] offset0:6 offset1:7
	ds_write_b64 v2, v[26:27] offset:4096
	s_waitcnt lgkmcnt(0)
	s_cmp_gt_i32 s43, 8
	s_waitcnt lgkmcnt(0)
	s_barrier
	s_cbranch_scc1 .LBB0_479
	s_load_dwordx2 s[6:7], s[58:59], 0x30
	s_mul_i32 s8, s0, 0xc000
	s_mul_hi_i32 s3, s0, 0xc000
	v_mov_b32_e32 v2, v0
	v_mov_b32_e32 v3, v4
	s_waitcnt lgkmcnt(0)
	s_add_u32 s6, s6, s8
	s_addc_u32 s3, s7, s3
	s_add_u32 s6, s6, s4
	s_addc_u32 s7, s3, s5
	v_lshl_add_u64 v[2:3], s[6:7], 0, v[2:3]
	s_add_i32 s3, s43, -8
	s_mul_hi_i32 s6, s0, 0x6c000
	s_mul_i32 s0, s0, 0x6c000
	s_mul_i32 s8, s43, 0xc000
	s_mul_hi_i32 s7, s43, 0xc000
	s_add_u32 s0, s0, s8
	s_addc_u32 s6, s6, s7
	s_add_u32 s4, s92, s4
	s_addc_u32 s5, s24, s5
	s_add_u32 s4, s4, s0
	s_addc_u32 s5, s5, s6
	s_lshl_b32 s0, s43, 9
	s_add_i32 s0, s0, 0
	s_add_i32 s0, s0, 0x10000
	v_lshl_add_u64 v[6:7], s[4:5], 0, v[0:1]
	v_add_u32_e32 v0, s0, v0
